# count the outstanding output stores in the LRU batch-loop and SSD chunk-loop waits (vmcnt N -> N+stores) + drop stale vmcnt(0) in phase-1 K loop
# baseline (speedup 1.0000x reference)
; #define PG8_STAGE(bufoff, gbase, voff) do { _Pragma("unroll") for (int _i = 0; _i < 2; ++_i) \
;         __builtin_amdgcn_global_load_lds((const unsigned*)((const char*)(gbase) + (voff)[_i]), (LAS unsigned*)(lds + (bufoff) + ldsw + _i * 8192), 16, 0, 0); } while (0)
; #define PG8_LDA(dst, b, h) do { _Pragma("unroll") for (int m = 0; m < 4; ++m) _Pragma("unroll") for (int k = 0; k < 2; ++k) dst[m][k] = *(const LAS bf16x8*)(lds + PG8_SA(b, h) + aoff + m * 2048 + k * 1024); } while (0)
; #define PG8_LDB(dst, b, h) do { _Pragma("unroll") for (int n = 0; n < 2; ++n) _Pragma("unroll") for (int k = 0; k < 2; ++k) dst[n][k] = *(const LAS bf16x8*)(lds + PG8_SB(b, h) + boff + n * 2048 + k * 1024); } while (0)
; #define PG8_MMA(ai, bj, At, Bt) do { __builtin_amdgcn_s_setprio(1); _Pragma("unroll") for (int m = 0; m < 4; ++m) _Pragma("unroll") for (int n = 0; n < 2; ++n) _Pragma("unroll") for (int k = 0; k < 2; ++k) \
;         acc[ai][bj][m][n] = __builtin_amdgcn_mfma_f32_16x16x32_bf16(Bt[n][k], At[m][k], acc[ai][bj][m][n], 0, 0, 0); __builtin_amdgcn_s_setprio(0); } while (0)
; #define PG8_WAIT_L(n) asm volatile("s_waitcnt lgkmcnt(" #n ")" ::: "memory")
; #define PG8_BAR __builtin_amdgcn_s_barrier()
; #define PG8_SCHED __builtin_amdgcn_sched_barrier(0)
; template <class Epi>
; __device__ __forceinline__ void gemm_phase(LAS unsigned char* lds, const Gemm g, const StaticOrder& S, const Epi& E) {
;     ...
;         for (int t = 0; t < nt; t += 2) {
;             const bool last = (t == nt - 2);
;             const char* a1 = cA + (size_t)(t + 1) * kstep;
;             const char* a2 = last ? nA : cA + (size_t)(t + 2) * kstep; const char* b2 = last ? nB : cB + (size_t)(t + 2) * kstep;
;             const char* a3 = a2 + kstep; const char* b3 = b2 + kstep;
;             if (last) E.pre(cur, wr, fr, epre);
;             PG8_LDB(B0, 0, 0); PG8_SCHED; PG8_LDA(At, 0, 0); PG8_STAGE(PG8_SA(1, 1), a1 + hstepA, voffA);
;             PG8_WAIT_L(8); PG8_BAR; PG8_WAIT_L(0); PG8_MMA(0, 0, At, B0); PG8_BAR; PG8_SCHED;
;             PG8_LDB(B1, 0, 1); PG8_STAGE(PG8_SB(0, 0), b2, voffB);
;             PG8_BAR; PG8_WAIT_L(0); PG8_MMA(0, 1, At, B1); PG8_BAR;
;             PG8_LDA(At, 0, 1); PG8_STAGE(PG8_SA(0, 0), a2, voffA);
;             PG8_BAR; PG8_WAIT_L(0); PG8_MMA(1, 0, At, B0); PG8_BAR; PG8_SCHED;
.LBB0_204:
	s_ashr_i32 s13, s12, 31
	v_cmp_lt_i64_e32 vcc, s[14:15], v[142:143]
	s_lshl_b64 s[14:15], s[12:13], 19
	s_add_u32 s14, s76, s14
	s_addc_u32 s15, s77, s15
	s_and_b64 s[16:17], vcc, exec
	s_cselect_b32 s13, s15, s21
	s_cselect_b32 s19, s14, s20
	s_ashr_i32 s11, s10, 31
	s_lshl_b64 s[16:17], s[10:11], 19
	s_add_u32 s16, s74, s16
	s_addc_u32 s17, s75, s17
	s_and_b64 s[24:25], vcc, exec
	s_cselect_b32 s11, s17, s23
	s_cselect_b32 s44, s16, s22
	s_add_u32 s20, s20, 0x40080
	s_addc_u32 s21, s21, 0
	s_add_u32 s45, s22, 0x100
	s_addc_u32 s46, s23, 0
	s_mov_b32 s47, -2
	s_waitcnt lgkmcnt(0)
	ds_read_b128 v[146:149], v170
	ds_read_b128 v[154:157], v170 offset:1024
	ds_read_b128 v[158:161], v170 offset:2048
	ds_read_b128 v[162:165], v170 offset:3072
	s_add_u32 s22, s20, 0xfffc0080
	s_addc_u32 s23, s21, -1
	s_cmp_eq_u32 s47, 12
	s_cselect_b32 s25, s13, s23
	s_cselect_b32 s24, s19, s22
	s_cselect_b32 s23, s11, s46
	s_cselect_b32 s22, s44, s45
	v_lshl_add_u64 v[150:151], s[20:21], 0, v[138:139]
	s_add_i32 m0, s30, 0xc000
	ds_read_b128 v[174:177], v171
	ds_read_b128 v[178:181], v171 offset:1024
	ds_read_b128 v[182:185], v171 offset:2048
	ds_read_b128 v[186:189], v171 offset:3072
	ds_read_b128 v[190:193], v171 offset:4096
	ds_read_b128 v[194:197], v171 offset:5120
	ds_read_b128 v[198:201], v171 offset:6144
	ds_read_b128 v[202:205], v171 offset:7168
	global_load_lds_dwordx4 v[150:151], off
	v_lshl_add_u64 v[150:151], s[20:21], 0, v[140:141]
	s_add_i32 m0, s30, 0xe000
	s_nop 0
	global_load_lds_dwordx4 v[150:151], off
	s_waitcnt lgkmcnt(8)
	s_barrier
	s_waitcnt lgkmcnt(0)
	s_setprio 1
	s_waitcnt lgkmcnt(0)
	v_mfma_f32_16x16x32_bf16 v[76:79], v[146:149], v[174:177], 0
	v_mfma_f32_16x16x32_bf16 v[64:67], v[158:161], v[174:177], 0
	v_mfma_f32_16x16x32_bf16 v[60:63], v[146:149], v[182:185], 0
	v_mfma_f32_16x16x32_bf16 v[56:59], v[158:161], v[182:185], 0
	v_mfma_f32_16x16x32_bf16 v[48:51], v[146:149], v[190:193], 0
	v_mfma_f32_16x16x32_bf16 v[40:43], v[158:161], v[190:193], 0
	v_mfma_f32_16x16x32_bf16 v[36:39], v[146:149], v[198:201], 0
	v_mfma_f32_16x16x32_bf16 v[32:35], v[158:161], v[198:201], 0
	v_mfma_f32_16x16x32_bf16 v[76:79], v[154:157], v[178:181], v[76:79]
	v_mfma_f32_16x16x32_bf16 v[64:67], v[162:165], v[178:181], v[64:67]
	v_mfma_f32_16x16x32_bf16 v[60:63], v[154:157], v[186:189], v[60:63]
	v_mfma_f32_16x16x32_bf16 v[56:59], v[162:165], v[186:189], v[56:59]
	v_mfma_f32_16x16x32_bf16 v[48:51], v[154:157], v[194:197], v[48:51]
	v_mfma_f32_16x16x32_bf16 v[40:43], v[162:165], v[194:197], v[40:43]
	v_mfma_f32_16x16x32_bf16 v[36:39], v[154:157], v[202:205], v[36:39]
	v_mfma_f32_16x16x32_bf16 v[32:35], v[162:165], v[202:205], v[32:35]
	s_setprio 0
	s_barrier
	s_add_i32 s48, s39, s27
	v_lshl_add_u64 v[150:151], s[22:23], 0, v[132:133]
	s_mov_b32 m0, s48
	ds_read_b128 v[206:209], v172
	ds_read_b128 v[210:213], v172 offset:1024
	ds_read_b128 v[214:217], v172 offset:2048
	ds_read_b128 v[218:221], v172 offset:3072
	global_load_lds_dwordx4 v[150:151], off
	v_lshl_add_u64 v[166:167], s[22:23], 0, v[128:129]
	s_add_i32 m0, s48, 0x2000
	s_nop 0
	global_load_lds_dwordx4 v[166:167], off
	s_barrier
	s_waitcnt lgkmcnt(0)
	s_setprio 1
	s_waitcnt lgkmcnt(0)
	v_mfma_f32_16x16x32_bf16 v[124:127], v[206:209], v[174:177], 0
	v_mfma_f32_16x16x32_bf16 v[120:123], v[214:217], v[174:177], 0
	v_mfma_f32_16x16x32_bf16 v[116:119], v[206:209], v[182:185], 0
	v_mfma_f32_16x16x32_bf16 v[112:115], v[214:217], v[182:185], 0
	v_mfma_f32_16x16x32_bf16 v[108:111], v[206:209], v[190:193], 0
	v_mfma_f32_16x16x32_bf16 v[104:107], v[214:217], v[190:193], 0
	v_mfma_f32_16x16x32_bf16 v[100:103], v[206:209], v[198:201], 0
	v_mfma_f32_16x16x32_bf16 v[96:99], v[214:217], v[198:201], 0
	v_mfma_f32_16x16x32_bf16 v[124:127], v[210:213], v[178:181], v[124:127]
	v_mfma_f32_16x16x32_bf16 v[120:123], v[218:221], v[178:181], v[120:123]
	v_mfma_f32_16x16x32_bf16 v[116:119], v[210:213], v[186:189], v[116:119]
	v_mfma_f32_16x16x32_bf16 v[112:115], v[218:221], v[186:189], v[112:115]
	v_mfma_f32_16x16x32_bf16 v[108:111], v[210:213], v[194:197], v[108:111]
	v_mfma_f32_16x16x32_bf16 v[104:107], v[218:221], v[194:197], v[104:107]
	v_mfma_f32_16x16x32_bf16 v[100:103], v[210:213], v[202:205], v[100:103]
	v_mfma_f32_16x16x32_bf16 v[96:99], v[218:221], v[202:205], v[96:99]
	s_setprio 0
	s_mov_b32 m0, s30
	v_lshl_add_u64 v[222:223], s[24:25], 0, v[134:135]
	s_barrier
	ds_read_b128 v[174:177], v171 offset:16384
	ds_read_b128 v[178:181], v171 offset:17408
	ds_read_b128 v[182:185], v171 offset:18432
	ds_read_b128 v[186:189], v171 offset:19456
	ds_read_b128 v[190:193], v171 offset:20480
	ds_read_b128 v[194:197], v171 offset:21504
	ds_read_b128 v[198:201], v171 offset:22528
	ds_read_b128 v[202:205], v171 offset:23552
	global_load_lds_dwordx4 v[222:223], off
	v_lshl_add_u64 v[224:225], s[24:25], 0, v[130:131]
	s_mov_b32 m0, s31
	s_nop 0
	global_load_lds_dwordx4 v[224:225], off
	s_barrier
	s_waitcnt lgkmcnt(0)
	s_setprio 1
	s_waitcnt lgkmcnt(0)
	v_mfma_f32_16x16x32_bf16 v[28:31], v[146:149], v[174:177], 0
	v_mfma_f32_16x16x32_bf16 v[24:27], v[158:161], v[174:177], 0
	v_mfma_f32_16x16x32_bf16 v[20:23], v[146:149], v[182:185], 0
	v_mfma_f32_16x16x32_bf16 v[16:19], v[158:161], v[182:185], 0
	v_mfma_f32_16x16x32_bf16 v[12:15], v[146:149], v[190:193], 0
	v_mfma_f32_16x16x32_bf16 v[8:11], v[158:161], v[190:193], 0
	v_mfma_f32_16x16x32_bf16 v[4:7], v[146:149], v[198:201], 0
	v_mfma_f32_16x16x32_bf16 v[0:3], v[158:161], v[198:201], 0
	v_mfma_f32_16x16x32_bf16 v[28:31], v[154:157], v[178:181], v[28:31]
	v_mfma_f32_16x16x32_bf16 v[24:27], v[162:165], v[178:181], v[24:27]
	v_mfma_f32_16x16x32_bf16 v[20:23], v[154:157], v[186:189], v[20:23]
	v_mfma_f32_16x16x32_bf16 v[16:19], v[162:165], v[186:189], v[16:19]
	v_mfma_f32_16x16x32_bf16 v[12:15], v[154:157], v[194:197], v[12:15]
	v_mfma_f32_16x16x32_bf16 v[8:11], v[162:165], v[194:197], v[8:11]
	v_mfma_f32_16x16x32_bf16 v[4:7], v[154:157], v[202:205], v[4:7]
	v_mfma_f32_16x16x32_bf16 v[0:3], v[162:165], v[202:205], v[0:3]
	s_setprio 0
	s_barrier
; #define PG8_STAGE(bufoff, gbase, voff) do { _Pragma("unroll") for (int _i = 0; _i < 2; ++_i) \
;         __builtin_amdgcn_global_load_lds((const unsigned*)((const char*)(gbase) + (voff)[_i]), (LAS unsigned*)(lds + (bufoff) + ldsw + _i * 8192), 16, 0, 0); } while (0)
; #define PG8_LDA(dst, b, h) do { _Pragma("unroll") for (int m = 0; m < 4; ++m) _Pragma("unroll") for (int k = 0; k < 2; ++k) dst[m][k] = *(const LAS bf16x8*)(lds + PG8_SA(b, h) + aoff + m * 2048 + k * 1024); } while (0)
; #define PG8_LDB(dst, b, h) do { _Pragma("unroll") for (int n = 0; n < 2; ++n) _Pragma("unroll") for (int k = 0; k < 2; ++k) dst[n][k] = *(const LAS bf16x8*)(lds + PG8_SB(b, h) + boff + n * 2048 + k * 1024); } while (0)
; #define PG8_MMA(ai, bj, At, Bt) do { __builtin_amdgcn_s_setprio(1); _Pragma("unroll") for (int m = 0; m < 4; ++m) _Pragma("unroll") for (int n = 0; n < 2; ++n) _Pragma("unroll") for (int k = 0; k < 2; ++k) \
;         acc[ai][bj][m][n] = __builtin_amdgcn_mfma_f32_16x16x32_bf16(Bt[n][k], At[m][k], acc[ai][bj][m][n], 0, 0, 0); __builtin_amdgcn_s_setprio(0); } while (0)
; #define PG8_WAIT_V(n) asm volatile("s_waitcnt vmcnt(" #n ")" ::: "memory")
; #define PG8_WAIT_L(n) asm volatile("s_waitcnt lgkmcnt(" #n ")" ::: "memory")
; #define PG8_BAR __builtin_amdgcn_s_barrier()
; #define PG8_SCHED __builtin_amdgcn_sched_barrier(0)
; template <class Epi>
; __device__ __forceinline__ void gemm_phase(LAS unsigned char* lds, const Gemm g, const StaticOrder& S, const Epi& E) {
;     ...
;             PG8_BAR; PG8_WAIT_L(0); PG8_MMA(1, 0, At, B0); PG8_BAR; PG8_SCHED;
;             PG8_STAGE(PG8_SB(0, 1), b2 + hstepB, voffB);
;             PG8_WAIT_V(6); PG8_BAR; PG8_MMA(1, 1, At, B1); PG8_BAR;
;             PG8_LDB(B0, 1, 0); PG8_SCHED; PG8_LDA(At, 1, 0); PG8_STAGE(PG8_SA(0, 1), a2 + hstepA, voffA);
;             PG8_WAIT_L(8); PG8_BAR; PG8_WAIT_L(0); PG8_MMA(0, 0, At, B0); PG8_BAR; PG8_SCHED;
;             PG8_LDB(B1, 1, 1); PG8_STAGE(PG8_SB(1, 0), b3, voffB);
;             PG8_BAR; PG8_WAIT_L(0); PG8_MMA(0, 1, At, B1); PG8_BAR;
;             PG8_LDA(At, 1, 1); PG8_STAGE(PG8_SA(1, 0), a3, voffA);
	s_add_u32 s48, s22, 0x40000
	s_addc_u32 s49, s23, 0
	s_add_i32 s50, s40, s27
	v_lshl_add_u64 v[146:147], s[48:49], 0, v[132:133]
	s_mov_b32 m0, s50
	s_nop 0
	global_load_lds_dwordx4 v[146:147], off
	v_lshl_add_u64 v[146:147], s[48:49], 0, v[128:129]
	s_add_i32 m0, s50, 0x2000
	s_nop 0
	global_load_lds_dwordx4 v[146:147], off
	s_waitcnt vmcnt(6)
	s_barrier
	s_setprio 1
	v_mfma_f32_16x16x32_bf16 v[92:95], v[206:209], v[174:177], 0
	v_mfma_f32_16x16x32_bf16 v[88:91], v[214:217], v[174:177], 0
	v_mfma_f32_16x16x32_bf16 v[84:87], v[206:209], v[182:185], 0
	v_mfma_f32_16x16x32_bf16 v[80:83], v[214:217], v[182:185], 0
	v_mfma_f32_16x16x32_bf16 v[72:75], v[206:209], v[190:193], 0
	v_mfma_f32_16x16x32_bf16 v[68:71], v[214:217], v[190:193], 0
	v_mfma_f32_16x16x32_bf16 v[52:55], v[206:209], v[198:201], 0
	v_mfma_f32_16x16x32_bf16 v[44:47], v[214:217], v[198:201], 0
	v_mfma_f32_16x16x32_bf16 v[92:95], v[210:213], v[178:181], v[92:95]
	v_mfma_f32_16x16x32_bf16 v[88:91], v[218:221], v[178:181], v[88:91]
	v_mfma_f32_16x16x32_bf16 v[84:87], v[210:213], v[186:189], v[84:87]
	v_mfma_f32_16x16x32_bf16 v[80:83], v[218:221], v[186:189], v[80:83]
	v_mfma_f32_16x16x32_bf16 v[72:75], v[210:213], v[194:197], v[72:75]
	v_mfma_f32_16x16x32_bf16 v[68:71], v[218:221], v[194:197], v[68:71]
	v_mfma_f32_16x16x32_bf16 v[52:55], v[210:213], v[202:205], v[52:55]
	v_mfma_f32_16x16x32_bf16 v[44:47], v[218:221], v[202:205], v[44:47]
	s_setprio 0
	s_add_i32 s48, 0, 0x18000
	v_add_u32_e32 v162, s48, v168
	s_barrier
	ds_read_b128 v[146:149], v162
	ds_read_b128 v[154:157], v162 offset:1024
	ds_read_b128 v[158:161], v162 offset:2048
	ds_read_b128 v[162:165], v162 offset:3072
	s_add_u32 s24, s24, 0x40000
	s_addc_u32 s25, s25, 0
	s_mov_b32 m0, s33
	v_lshl_add_u64 v[206:207], s[24:25], 0, v[134:135]
	ds_read_b128 v[174:177], v171 offset:32768
	ds_read_b128 v[178:181], v171 offset:33792
	ds_read_b128 v[182:185], v171 offset:34816
	ds_read_b128 v[186:189], v171 offset:35840
	ds_read_b128 v[190:193], v171 offset:36864
	ds_read_b128 v[194:197], v171 offset:37888
	ds_read_b128 v[198:201], v171 offset:38912
	ds_read_b128 v[202:205], v171 offset:39936
	global_load_lds_dwordx4 v[206:207], off
	v_lshl_add_u64 v[206:207], s[24:25], 0, v[130:131]
	s_mov_b32 m0, s34
	s_nop 0
	global_load_lds_dwordx4 v[206:207], off
	s_waitcnt lgkmcnt(8)
	s_barrier
	s_waitcnt lgkmcnt(0)
	s_setprio 1
	s_waitcnt lgkmcnt(0)
	v_mfma_f32_16x16x32_bf16 v[76:79], v[146:149], v[174:177], v[76:79]
	v_mfma_f32_16x16x32_bf16 v[64:67], v[158:161], v[174:177], v[64:67]
	v_mfma_f32_16x16x32_bf16 v[60:63], v[146:149], v[182:185], v[60:63]
	v_mfma_f32_16x16x32_bf16 v[56:59], v[158:161], v[182:185], v[56:59]
	v_mfma_f32_16x16x32_bf16 v[48:51], v[146:149], v[190:193], v[48:51]
	v_mfma_f32_16x16x32_bf16 v[40:43], v[158:161], v[190:193], v[40:43]
	v_mfma_f32_16x16x32_bf16 v[36:39], v[146:149], v[198:201], v[36:39]
	v_mfma_f32_16x16x32_bf16 v[32:35], v[158:161], v[198:201], v[32:35]
	v_mfma_f32_16x16x32_bf16 v[76:79], v[154:157], v[178:181], v[76:79]
	v_mfma_f32_16x16x32_bf16 v[64:67], v[162:165], v[178:181], v[64:67]
	v_mfma_f32_16x16x32_bf16 v[60:63], v[154:157], v[186:189], v[60:63]
	v_mfma_f32_16x16x32_bf16 v[56:59], v[162:165], v[186:189], v[56:59]
	v_mfma_f32_16x16x32_bf16 v[48:51], v[154:157], v[194:197], v[48:51]
	v_mfma_f32_16x16x32_bf16 v[40:43], v[162:165], v[194:197], v[40:43]
	v_mfma_f32_16x16x32_bf16 v[36:39], v[154:157], v[202:205], v[36:39]
	v_mfma_f32_16x16x32_bf16 v[32:35], v[162:165], v[202:205], v[32:35]
	s_setprio 0
	s_barrier
	s_add_i32 s24, 0, 0x1c000
	s_add_i32 s25, s48, s27
	v_add_u32_e32 v218, s24, v168
	v_lshl_add_u64 v[150:151], v[150:151], 0, s[6:7]
	s_mov_b32 m0, s25
	ds_read_b128 v[206:209], v218
	ds_read_b128 v[210:213], v218 offset:1024
	ds_read_b128 v[214:217], v218 offset:2048
	ds_read_b128 v[218:221], v218 offset:3072
	global_load_lds_dwordx4 v[150:151], off
	v_lshl_add_u64 v[150:151], v[166:167], 0, s[6:7]
	s_add_i32 m0, s25, 0x2000
	s_nop 0
	global_load_lds_dwordx4 v[150:151], off
	s_barrier
	s_waitcnt lgkmcnt(0)
	s_setprio 1
	s_waitcnt lgkmcnt(0)
	v_mfma_f32_16x16x32_bf16 v[124:127], v[206:209], v[174:177], v[124:127]
	v_mfma_f32_16x16x32_bf16 v[120:123], v[214:217], v[174:177], v[120:123]
	v_mfma_f32_16x16x32_bf16 v[116:119], v[206:209], v[182:185], v[116:119]
	v_mfma_f32_16x16x32_bf16 v[112:115], v[214:217], v[182:185], v[112:115]
	v_mfma_f32_16x16x32_bf16 v[108:111], v[206:209], v[190:193], v[108:111]
	v_mfma_f32_16x16x32_bf16 v[104:107], v[214:217], v[190:193], v[104:107]
	v_mfma_f32_16x16x32_bf16 v[100:103], v[206:209], v[198:201], v[100:103]
	v_mfma_f32_16x16x32_bf16 v[96:99], v[214:217], v[198:201], v[96:99]
	v_mfma_f32_16x16x32_bf16 v[124:127], v[210:213], v[178:181], v[124:127]
	v_mfma_f32_16x16x32_bf16 v[120:123], v[218:221], v[178:181], v[120:123]
	v_mfma_f32_16x16x32_bf16 v[116:119], v[210:213], v[186:189], v[116:119]
	v_mfma_f32_16x16x32_bf16 v[112:115], v[218:221], v[186:189], v[112:115]
	v_mfma_f32_16x16x32_bf16 v[108:111], v[210:213], v[194:197], v[108:111]
	v_mfma_f32_16x16x32_bf16 v[104:107], v[218:221], v[194:197], v[104:107]
	v_mfma_f32_16x16x32_bf16 v[100:103], v[210:213], v[202:205], v[100:103]
	v_mfma_f32_16x16x32_bf16 v[96:99], v[218:221], v[202:205], v[96:99]
	s_setprio 0
	s_mov_b32 m0, s36
	v_lshl_add_u64 v[150:151], v[222:223], 0, s[6:7]
	s_barrier
	ds_read_b128 v[174:177], v171 offset:49152
	ds_read_b128 v[178:181], v171 offset:50176
	ds_read_b128 v[182:185], v171 offset:51200
	ds_read_b128 v[186:189], v171 offset:52224
	ds_read_b128 v[190:193], v171 offset:53248
	ds_read_b128 v[194:197], v171 offset:54272
	ds_read_b128 v[198:201], v171 offset:55296
	ds_read_b128 v[202:205], v171 offset:56320
	global_load_lds_dwordx4 v[150:151], off
	v_lshl_add_u64 v[150:151], v[224:225], 0, s[6:7]
	s_mov_b32 m0, s37
	s_nop 0
	global_load_lds_dwordx4 v[150:151], off
	s_barrier
; #define PG8_STAGE(bufoff, gbase, voff) do { _Pragma("unroll") for (int _i = 0; _i < 2; ++_i) \
;         __builtin_amdgcn_global_load_lds((const unsigned*)((const char*)(gbase) + (voff)[_i]), (LAS unsigned*)(lds + (bufoff) + ldsw + _i * 8192), 16, 0, 0); } while (0)
; #define PG8_LDA(dst, b, h) do { _Pragma("unroll") for (int m = 0; m < 4; ++m) _Pragma("unroll") for (int k = 0; k < 2; ++k) dst[m][k] = *(const LAS bf16x8*)(lds + PG8_SA(b, h) + aoff + m * 2048 + k * 1024); } while (0)
; #define PG8_LDB(dst, b, h) do { _Pragma("unroll") for (int n = 0; n < 2; ++n) _Pragma("unroll") for (int k = 0; k < 2; ++k) dst[n][k] = *(const LAS bf16x8*)(lds + PG8_SB(b, h) + boff + n * 2048 + k * 1024); } while (0)
; #define PG8_WAIT_V(n) asm volatile("s_waitcnt vmcnt(" #n ")" ::: "memory")
; #define PG8_WAIT_L(n) asm volatile("s_waitcnt lgkmcnt(" #n ")" ::: "memory")
; #define PG8_BAR __builtin_amdgcn_s_barrier()
; #define PG8_SCHED __builtin_amdgcn_sched_barrier(0)
; template <class Epi>
; __device__ __forceinline__ void gemm_phase(LAS unsigned char* lds, const Gemm g, const StaticOrder& S, const Epi& E) {
;     ...
;             PG8_LDB(B0, 0, 0); PG8_SCHED; PG8_LDA(At, 0, 0); PG8_STAGE(PG8_SA(1, 1), a1 + hstepA, voffA);
;             PG8_WAIT_L(8); PG8_BAR; PG8_WAIT_L(0); PG8_MMA(0, 0, At, B0); PG8_BAR; PG8_SCHED;
;             PG8_LDB(B1, 0, 1); PG8_STAGE(PG8_SB(0, 0), b2, voffB);
;             PG8_BAR; PG8_WAIT_L(0); PG8_MMA(0, 1, At, B1); PG8_BAR;
;             PG8_LDA(At, 0, 1); PG8_STAGE(PG8_SA(0, 0), a2, voffA);
;             PG8_BAR; PG8_WAIT_L(0); PG8_MMA(1, 0, At, B0); PG8_BAR; PG8_SCHED;
;             PG8_STAGE(PG8_SB(0, 1), b2 + hstepB, voffB);
;             PG8_WAIT_V(6); PG8_BAR; PG8_MMA(1, 1, At, B1); PG8_BAR;
;             PG8_LDB(B0, 1, 0); PG8_SCHED; PG8_LDA(At, 1, 0); PG8_STAGE(PG8_SA(0, 1), a2 + hstepA, voffA);
;             PG8_WAIT_L(8); PG8_BAR; PG8_WAIT_L(0); PG8_MMA(0, 0, At, B0); PG8_BAR; PG8_SCHED;
;             PG8_LDB(B1, 1, 1); PG8_STAGE(PG8_SB(1, 0), b3, voffB);
;             PG8_BAR; PG8_WAIT_L(0); PG8_MMA(0, 1, At, B1); PG8_BAR;
;             PG8_LDA(At, 1, 1); PG8_STAGE(PG8_SA(1, 0), a3, voffA);
;             PG8_BAR; PG8_WAIT_L(0); PG8_MMA(1, 0, At, B0); PG8_BAR; PG8_SCHED;
;             PG8_STAGE(PG8_SB(1, 1), b3 + hstepB, voffB);
;             PG8_WAIT_V(6); PG8_BAR; PG8_MMA(1, 1, At, B1); PG8_BAR;
	s_waitcnt lgkmcnt(0)
	s_setprio 1
	s_waitcnt lgkmcnt(0)
	v_mfma_f32_16x16x32_bf16 v[28:31], v[146:149], v[174:177], v[28:31]
	v_mfma_f32_16x16x32_bf16 v[24:27], v[158:161], v[174:177], v[24:27]
	v_mfma_f32_16x16x32_bf16 v[20:23], v[146:149], v[182:185], v[20:23]
	v_mfma_f32_16x16x32_bf16 v[16:19], v[158:161], v[182:185], v[16:19]
	v_mfma_f32_16x16x32_bf16 v[12:15], v[146:149], v[190:193], v[12:15]
	v_mfma_f32_16x16x32_bf16 v[8:11], v[158:161], v[190:193], v[8:11]
	v_mfma_f32_16x16x32_bf16 v[4:7], v[146:149], v[198:201], v[4:7]
	v_mfma_f32_16x16x32_bf16 v[0:3], v[158:161], v[198:201], v[0:3]
	v_mfma_f32_16x16x32_bf16 v[28:31], v[154:157], v[178:181], v[28:31]
	v_mfma_f32_16x16x32_bf16 v[24:27], v[162:165], v[178:181], v[24:27]
	v_mfma_f32_16x16x32_bf16 v[20:23], v[154:157], v[186:189], v[20:23]
	v_mfma_f32_16x16x32_bf16 v[16:19], v[162:165], v[186:189], v[16:19]
	v_mfma_f32_16x16x32_bf16 v[12:15], v[154:157], v[194:197], v[12:15]
	v_mfma_f32_16x16x32_bf16 v[8:11], v[162:165], v[194:197], v[8:11]
	v_mfma_f32_16x16x32_bf16 v[4:7], v[154:157], v[202:205], v[4:7]
	v_mfma_f32_16x16x32_bf16 v[0:3], v[162:165], v[202:205], v[0:3]
	s_setprio 0
	s_barrier
	s_add_u32 s22, s22, 0x40080
	s_addc_u32 s23, s23, 0
	s_add_i32 s24, s24, s27
	v_lshl_add_u64 v[146:147], s[22:23], 0, v[132:133]
	s_mov_b32 m0, s24
	s_nop 0
	global_load_lds_dwordx4 v[146:147], off
	v_lshl_add_u64 v[146:147], s[22:23], 0, v[128:129]
	s_add_i32 m0, s24, 0x2000
	s_nop 0
	global_load_lds_dwordx4 v[146:147], off
	s_waitcnt vmcnt(6)
	s_barrier
	s_setprio 1
	v_mfma_f32_16x16x32_bf16 v[92:95], v[206:209], v[174:177], v[92:95]
	v_mfma_f32_16x16x32_bf16 v[88:91], v[214:217], v[174:177], v[88:91]
	v_mfma_f32_16x16x32_bf16 v[84:87], v[206:209], v[182:185], v[84:87]
	v_mfma_f32_16x16x32_bf16 v[80:83], v[214:217], v[182:185], v[80:83]
	v_mfma_f32_16x16x32_bf16 v[72:75], v[206:209], v[190:193], v[72:75]
	v_mfma_f32_16x16x32_bf16 v[68:71], v[214:217], v[190:193], v[68:71]
	v_mfma_f32_16x16x32_bf16 v[52:55], v[206:209], v[198:201], v[52:55]
	v_mfma_f32_16x16x32_bf16 v[44:47], v[214:217], v[198:201], v[44:47]
	v_mfma_f32_16x16x32_bf16 v[92:95], v[210:213], v[178:181], v[92:95]
	v_mfma_f32_16x16x32_bf16 v[88:91], v[218:221], v[178:181], v[88:91]
	v_mfma_f32_16x16x32_bf16 v[84:87], v[210:213], v[186:189], v[84:87]
	v_mfma_f32_16x16x32_bf16 v[80:83], v[218:221], v[186:189], v[80:83]
	v_mfma_f32_16x16x32_bf16 v[72:75], v[210:213], v[194:197], v[72:75]
	v_mfma_f32_16x16x32_bf16 v[68:71], v[218:221], v[194:197], v[68:71]
	v_mfma_f32_16x16x32_bf16 v[52:55], v[210:213], v[202:205], v[52:55]
	v_mfma_f32_16x16x32_bf16 v[44:47], v[218:221], v[202:205], v[44:47]
	s_setprio 0
	s_add_i32 s47, s47, 2
	s_add_u32 s20, s20, 0x100
	s_addc_u32 s21, s21, 0
	s_add_u32 s45, s45, 0x100
	s_addc_u32 s46, s46, 0
	s_cmp_gt_u32 s47, 13
	s_barrier
.LBB0_205:
	ds_read_b128 v[146:149], v170
	ds_read_b128 v[154:157], v170 offset:1024
	ds_read_b128 v[158:161], v170 offset:2048
	ds_read_b128 v[162:165], v170 offset:3072
	s_add_u32 s22, s20, 0xfffc0080
	s_addc_u32 s23, s21, -1
	s_cmp_eq_u32 s47, 12
	s_cselect_b32 s25, s13, s23
	s_cselect_b32 s24, s19, s22
	s_cselect_b32 s23, s11, s46
	s_cselect_b32 s22, s44, s45
	v_lshl_add_u64 v[150:151], s[20:21], 0, v[138:139]
	s_add_i32 m0, s30, 0xc000
	ds_read_b128 v[174:177], v171
	ds_read_b128 v[178:181], v171 offset:1024
	ds_read_b128 v[182:185], v171 offset:2048
	ds_read_b128 v[186:189], v171 offset:3072
	ds_read_b128 v[190:193], v171 offset:4096
	ds_read_b128 v[194:197], v171 offset:5120
	ds_read_b128 v[198:201], v171 offset:6144
	ds_read_b128 v[202:205], v171 offset:7168
	global_load_lds_dwordx4 v[150:151], off
	v_lshl_add_u64 v[150:151], s[20:21], 0, v[140:141]
	s_add_i32 m0, s30, 0xe000
	s_nop 0
	global_load_lds_dwordx4 v[150:151], off
	s_waitcnt lgkmcnt(8)
	s_barrier
	s_waitcnt lgkmcnt(0)
	s_setprio 1
	s_waitcnt lgkmcnt(0)
	v_mfma_f32_16x16x32_bf16 v[76:79], v[146:149], v[174:177], v[76:79]
	v_mfma_f32_16x16x32_bf16 v[64:67], v[158:161], v[174:177], v[64:67]
	v_mfma_f32_16x16x32_bf16 v[60:63], v[146:149], v[182:185], v[60:63]
	v_mfma_f32_16x16x32_bf16 v[56:59], v[158:161], v[182:185], v[56:59]
	v_mfma_f32_16x16x32_bf16 v[48:51], v[146:149], v[190:193], v[48:51]
	v_mfma_f32_16x16x32_bf16 v[40:43], v[158:161], v[190:193], v[40:43]
	v_mfma_f32_16x16x32_bf16 v[36:39], v[146:149], v[198:201], v[36:39]
	v_mfma_f32_16x16x32_bf16 v[32:35], v[158:161], v[198:201], v[32:35]
	v_mfma_f32_16x16x32_bf16 v[76:79], v[154:157], v[178:181], v[76:79]
	v_mfma_f32_16x16x32_bf16 v[64:67], v[162:165], v[178:181], v[64:67]
	v_mfma_f32_16x16x32_bf16 v[60:63], v[154:157], v[186:189], v[60:63]
	v_mfma_f32_16x16x32_bf16 v[56:59], v[162:165], v[186:189], v[56:59]
	v_mfma_f32_16x16x32_bf16 v[48:51], v[154:157], v[194:197], v[48:51]
	v_mfma_f32_16x16x32_bf16 v[40:43], v[162:165], v[194:197], v[40:43]
	v_mfma_f32_16x16x32_bf16 v[36:39], v[154:157], v[202:205], v[36:39]
	v_mfma_f32_16x16x32_bf16 v[32:35], v[162:165], v[202:205], v[32:35]
	s_setprio 0
	s_barrier
	s_add_i32 s48, s39, s27
	v_lshl_add_u64 v[150:151], s[22:23], 0, v[132:133]
	s_mov_b32 m0, s48
	ds_read_b128 v[206:209], v172
	ds_read_b128 v[210:213], v172 offset:1024
	ds_read_b128 v[214:217], v172 offset:2048
	ds_read_b128 v[218:221], v172 offset:3072
	global_load_lds_dwordx4 v[150:151], off
	v_lshl_add_u64 v[166:167], s[22:23], 0, v[128:129]
	s_add_i32 m0, s48, 0x2000
	s_nop 0
	global_load_lds_dwordx4 v[166:167], off
	s_barrier
; #define PG8_STAGE(bufoff, gbase, voff) do { _Pragma("unroll") for (int _i = 0; _i < 2; ++_i) \
;         __builtin_amdgcn_global_load_lds((const unsigned*)((const char*)(gbase) + (voff)[_i]), (LAS unsigned*)(lds + (bufoff) + ldsw + _i * 8192), 16, 0, 0); } while (0)
; #define PG8_LDA(dst, b, h) do { _Pragma("unroll") for (int m = 0; m < 4; ++m) _Pragma("unroll") for (int k = 0; k < 2; ++k) dst[m][k] = *(const LAS bf16x8*)(lds + PG8_SA(b, h) + aoff + m * 2048 + k * 1024); } while (0)
; #define PG8_LDB(dst, b, h) do { _Pragma("unroll") for (int n = 0; n < 2; ++n) _Pragma("unroll") for (int k = 0; k < 2; ++k) dst[n][k] = *(const LAS bf16x8*)(lds + PG8_SB(b, h) + boff + n * 2048 + k * 1024); } while (0)
; #define PG8_MMA(ai, bj, At, Bt) do { __builtin_amdgcn_s_setprio(1); _Pragma("unroll") for (int m = 0; m < 4; ++m) _Pragma("unroll") for (int n = 0; n < 2; ++n) _Pragma("unroll") for (int k = 0; k < 2; ++k) \
;         acc[ai][bj][m][n] = __builtin_amdgcn_mfma_f32_16x16x32_bf16(Bt[n][k], At[m][k], acc[ai][bj][m][n], 0, 0, 0); __builtin_amdgcn_s_setprio(0); } while (0)
; #define PG8_WAIT_V(n) asm volatile("s_waitcnt vmcnt(" #n ")" ::: "memory")
; #define PG8_WAIT_L(n) asm volatile("s_waitcnt lgkmcnt(" #n ")" ::: "memory")
; #define PG8_BAR __builtin_amdgcn_s_barrier()
; #define PG8_SCHED __builtin_amdgcn_sched_barrier(0)
; template <class Epi>
; __device__ __forceinline__ void gemm_phase(LAS unsigned char* lds, const Gemm g, const StaticOrder& S, const Epi& E) {
;     ...
;             PG8_BAR; PG8_WAIT_L(0); PG8_MMA(0, 1, At, B1); PG8_BAR;
;             PG8_LDA(At, 0, 1); PG8_STAGE(PG8_SA(0, 0), a2, voffA);
;             PG8_BAR; PG8_WAIT_L(0); PG8_MMA(1, 0, At, B0); PG8_BAR; PG8_SCHED;
;             PG8_STAGE(PG8_SB(0, 1), b2 + hstepB, voffB);
;             PG8_WAIT_V(6); PG8_BAR; PG8_MMA(1, 1, At, B1); PG8_BAR;
;             PG8_LDB(B0, 1, 0); PG8_SCHED; PG8_LDA(At, 1, 0); PG8_STAGE(PG8_SA(0, 1), a2 + hstepA, voffA);
;             PG8_WAIT_L(8); PG8_BAR; PG8_WAIT_L(0); PG8_MMA(0, 0, At, B0); PG8_BAR; PG8_SCHED;
;             PG8_LDB(B1, 1, 1); PG8_STAGE(PG8_SB(1, 0), b3, voffB);
;             PG8_BAR; PG8_WAIT_L(0); PG8_MMA(0, 1, At, B1); PG8_BAR;
;             PG8_LDA(At, 1, 1); PG8_STAGE(PG8_SA(1, 0), a3, voffA);
	s_waitcnt lgkmcnt(0)
	s_setprio 1
	s_waitcnt lgkmcnt(0)
	v_mfma_f32_16x16x32_bf16 v[124:127], v[206:209], v[174:177], v[124:127]
	v_mfma_f32_16x16x32_bf16 v[120:123], v[214:217], v[174:177], v[120:123]
	v_mfma_f32_16x16x32_bf16 v[116:119], v[206:209], v[182:185], v[116:119]
	v_mfma_f32_16x16x32_bf16 v[112:115], v[214:217], v[182:185], v[112:115]
	v_mfma_f32_16x16x32_bf16 v[108:111], v[206:209], v[190:193], v[108:111]
	v_mfma_f32_16x16x32_bf16 v[104:107], v[214:217], v[190:193], v[104:107]
	v_mfma_f32_16x16x32_bf16 v[100:103], v[206:209], v[198:201], v[100:103]
	v_mfma_f32_16x16x32_bf16 v[96:99], v[214:217], v[198:201], v[96:99]
	v_mfma_f32_16x16x32_bf16 v[124:127], v[210:213], v[178:181], v[124:127]
	v_mfma_f32_16x16x32_bf16 v[120:123], v[218:221], v[178:181], v[120:123]
	v_mfma_f32_16x16x32_bf16 v[116:119], v[210:213], v[186:189], v[116:119]
	v_mfma_f32_16x16x32_bf16 v[112:115], v[218:221], v[186:189], v[112:115]
	v_mfma_f32_16x16x32_bf16 v[108:111], v[210:213], v[194:197], v[108:111]
	v_mfma_f32_16x16x32_bf16 v[104:107], v[218:221], v[194:197], v[104:107]
	v_mfma_f32_16x16x32_bf16 v[100:103], v[210:213], v[202:205], v[100:103]
	v_mfma_f32_16x16x32_bf16 v[96:99], v[218:221], v[202:205], v[96:99]
	s_setprio 0
	s_mov_b32 m0, s30
	v_lshl_add_u64 v[222:223], s[24:25], 0, v[134:135]
	s_barrier
	ds_read_b128 v[174:177], v171 offset:16384
	ds_read_b128 v[178:181], v171 offset:17408
	ds_read_b128 v[182:185], v171 offset:18432
	ds_read_b128 v[186:189], v171 offset:19456
	ds_read_b128 v[190:193], v171 offset:20480
	ds_read_b128 v[194:197], v171 offset:21504
	ds_read_b128 v[198:201], v171 offset:22528
	ds_read_b128 v[202:205], v171 offset:23552
	global_load_lds_dwordx4 v[222:223], off
	v_lshl_add_u64 v[224:225], s[24:25], 0, v[130:131]
	s_mov_b32 m0, s31
	s_nop 0
	global_load_lds_dwordx4 v[224:225], off
	s_barrier
	s_waitcnt lgkmcnt(0)
	s_setprio 1
	s_waitcnt lgkmcnt(0)
	v_mfma_f32_16x16x32_bf16 v[28:31], v[146:149], v[174:177], v[28:31]
	v_mfma_f32_16x16x32_bf16 v[24:27], v[158:161], v[174:177], v[24:27]
	v_mfma_f32_16x16x32_bf16 v[20:23], v[146:149], v[182:185], v[20:23]
	v_mfma_f32_16x16x32_bf16 v[16:19], v[158:161], v[182:185], v[16:19]
	v_mfma_f32_16x16x32_bf16 v[12:15], v[146:149], v[190:193], v[12:15]
	v_mfma_f32_16x16x32_bf16 v[8:11], v[158:161], v[190:193], v[8:11]
	v_mfma_f32_16x16x32_bf16 v[4:7], v[146:149], v[198:201], v[4:7]
	v_mfma_f32_16x16x32_bf16 v[0:3], v[158:161], v[198:201], v[0:3]
	v_mfma_f32_16x16x32_bf16 v[28:31], v[154:157], v[178:181], v[28:31]
	v_mfma_f32_16x16x32_bf16 v[24:27], v[162:165], v[178:181], v[24:27]
	v_mfma_f32_16x16x32_bf16 v[20:23], v[154:157], v[186:189], v[20:23]
	v_mfma_f32_16x16x32_bf16 v[16:19], v[162:165], v[186:189], v[16:19]
	v_mfma_f32_16x16x32_bf16 v[12:15], v[154:157], v[194:197], v[12:15]
	v_mfma_f32_16x16x32_bf16 v[8:11], v[162:165], v[194:197], v[8:11]
	v_mfma_f32_16x16x32_bf16 v[4:7], v[154:157], v[202:205], v[4:7]
	v_mfma_f32_16x16x32_bf16 v[0:3], v[162:165], v[202:205], v[0:3]
	s_setprio 0
	s_barrier
	s_add_u32 s48, s22, 0x40000
	s_addc_u32 s49, s23, 0
	s_add_i32 s50, s40, s27
	v_lshl_add_u64 v[146:147], s[48:49], 0, v[132:133]
	s_mov_b32 m0, s50
	s_nop 0
	global_load_lds_dwordx4 v[146:147], off
	v_lshl_add_u64 v[146:147], s[48:49], 0, v[128:129]
	s_add_i32 m0, s50, 0x2000
	s_nop 0
	global_load_lds_dwordx4 v[146:147], off
	s_waitcnt vmcnt(6)
	s_barrier
	s_setprio 1
	v_mfma_f32_16x16x32_bf16 v[92:95], v[206:209], v[174:177], v[92:95]
	v_mfma_f32_16x16x32_bf16 v[88:91], v[214:217], v[174:177], v[88:91]
	v_mfma_f32_16x16x32_bf16 v[84:87], v[206:209], v[182:185], v[84:87]
	v_mfma_f32_16x16x32_bf16 v[80:83], v[214:217], v[182:185], v[80:83]
	v_mfma_f32_16x16x32_bf16 v[72:75], v[206:209], v[190:193], v[72:75]
	v_mfma_f32_16x16x32_bf16 v[68:71], v[214:217], v[190:193], v[68:71]
	v_mfma_f32_16x16x32_bf16 v[52:55], v[206:209], v[198:201], v[52:55]
	v_mfma_f32_16x16x32_bf16 v[44:47], v[214:217], v[198:201], v[44:47]
	v_mfma_f32_16x16x32_bf16 v[92:95], v[210:213], v[178:181], v[92:95]
	v_mfma_f32_16x16x32_bf16 v[88:91], v[218:221], v[178:181], v[88:91]
	v_mfma_f32_16x16x32_bf16 v[84:87], v[210:213], v[186:189], v[84:87]
	v_mfma_f32_16x16x32_bf16 v[80:83], v[218:221], v[186:189], v[80:83]
	v_mfma_f32_16x16x32_bf16 v[72:75], v[210:213], v[194:197], v[72:75]
	v_mfma_f32_16x16x32_bf16 v[68:71], v[218:221], v[194:197], v[68:71]
	v_mfma_f32_16x16x32_bf16 v[52:55], v[210:213], v[202:205], v[52:55]
	v_mfma_f32_16x16x32_bf16 v[44:47], v[218:221], v[202:205], v[44:47]
	s_setprio 0
	s_add_i32 s48, 0, 0x18000
	v_add_u32_e32 v162, s48, v168
	s_barrier
	ds_read_b128 v[146:149], v162
	ds_read_b128 v[154:157], v162 offset:1024
	ds_read_b128 v[158:161], v162 offset:2048
	ds_read_b128 v[162:165], v162 offset:3072
	s_add_u32 s24, s24, 0x40000
	s_addc_u32 s25, s25, 0
	s_mov_b32 m0, s33
	v_lshl_add_u64 v[206:207], s[24:25], 0, v[134:135]
	ds_read_b128 v[174:177], v171 offset:32768
	ds_read_b128 v[178:181], v171 offset:33792
	ds_read_b128 v[182:185], v171 offset:34816
	ds_read_b128 v[186:189], v171 offset:35840
	ds_read_b128 v[190:193], v171 offset:36864
	ds_read_b128 v[194:197], v171 offset:37888
	ds_read_b128 v[198:201], v171 offset:38912
	ds_read_b128 v[202:205], v171 offset:39936
	global_load_lds_dwordx4 v[206:207], off
	v_lshl_add_u64 v[206:207], s[24:25], 0, v[130:131]
	s_mov_b32 m0, s34
	s_nop 0
	global_load_lds_dwordx4 v[206:207], off
	s_waitcnt lgkmcnt(8)
	s_barrier
; #define PG8_STAGE(bufoff, gbase, voff) do { _Pragma("unroll") for (int _i = 0; _i < 2; ++_i) \
;         __builtin_amdgcn_global_load_lds((const unsigned*)((const char*)(gbase) + (voff)[_i]), (LAS unsigned*)(lds + (bufoff) + ldsw + _i * 8192), 16, 0, 0); } while (0)
; #define PG8_LDA(dst, b, h) do { _Pragma("unroll") for (int m = 0; m < 4; ++m) _Pragma("unroll") for (int k = 0; k < 2; ++k) dst[m][k] = *(const LAS bf16x8*)(lds + PG8_SA(b, h) + aoff + m * 2048 + k * 1024); } while (0)
; #define PG8_LDB(dst, b, h) do { _Pragma("unroll") for (int n = 0; n < 2; ++n) _Pragma("unroll") for (int k = 0; k < 2; ++k) dst[n][k] = *(const LAS bf16x8*)(lds + PG8_SB(b, h) + boff + n * 2048 + k * 1024); } while (0)
; #define PG8_MMA(ai, bj, At, Bt) do { __builtin_amdgcn_s_setprio(1); _Pragma("unroll") for (int m = 0; m < 4; ++m) _Pragma("unroll") for (int n = 0; n < 2; ++n) _Pragma("unroll") for (int k = 0; k < 2; ++k) \
;         acc[ai][bj][m][n] = __builtin_amdgcn_mfma_f32_16x16x32_bf16(Bt[n][k], At[m][k], acc[ai][bj][m][n], 0, 0, 0); __builtin_amdgcn_s_setprio(0); } while (0)
; #define PG8_WAIT_V(n) asm volatile("s_waitcnt vmcnt(" #n ")" ::: "memory")
; #define PG8_WAIT_L(n) asm volatile("s_waitcnt lgkmcnt(" #n ")" ::: "memory")
; #define PG8_BAR __builtin_amdgcn_s_barrier()
; #define PG8_SCHED __builtin_amdgcn_sched_barrier(0)
; template <class Epi>
; __device__ __forceinline__ void gemm_phase(LAS unsigned char* lds, const Gemm g, const StaticOrder& S, const Epi& E) {
;     ...
;             PG8_LDB(B0, 1, 0); PG8_SCHED; PG8_LDA(At, 1, 0); PG8_STAGE(PG8_SA(0, 1), a2 + hstepA, voffA);
;             PG8_WAIT_L(8); PG8_BAR; PG8_WAIT_L(0); PG8_MMA(0, 0, At, B0); PG8_BAR; PG8_SCHED;
;             PG8_LDB(B1, 1, 1); PG8_STAGE(PG8_SB(1, 0), b3, voffB);
;             PG8_BAR; PG8_WAIT_L(0); PG8_MMA(0, 1, At, B1); PG8_BAR;
;             PG8_LDA(At, 1, 1); PG8_STAGE(PG8_SA(1, 0), a3, voffA);
;             PG8_BAR; PG8_WAIT_L(0); PG8_MMA(1, 0, At, B0); PG8_BAR; PG8_SCHED;
;             PG8_STAGE(PG8_SB(1, 1), b3 + hstepB, voffB);
;             PG8_WAIT_V(6); PG8_BAR; PG8_MMA(1, 1, At, B1); PG8_BAR;
	s_waitcnt lgkmcnt(0)
	s_setprio 1
	s_waitcnt lgkmcnt(0)
	v_mfma_f32_16x16x32_bf16 v[76:79], v[146:149], v[174:177], v[76:79]
	v_mfma_f32_16x16x32_bf16 v[64:67], v[158:161], v[174:177], v[64:67]
	v_mfma_f32_16x16x32_bf16 v[60:63], v[146:149], v[182:185], v[60:63]
	v_mfma_f32_16x16x32_bf16 v[56:59], v[158:161], v[182:185], v[56:59]
	v_mfma_f32_16x16x32_bf16 v[48:51], v[146:149], v[190:193], v[48:51]
	v_mfma_f32_16x16x32_bf16 v[40:43], v[158:161], v[190:193], v[40:43]
	v_mfma_f32_16x16x32_bf16 v[36:39], v[146:149], v[198:201], v[36:39]
	v_mfma_f32_16x16x32_bf16 v[32:35], v[158:161], v[198:201], v[32:35]
	v_mfma_f32_16x16x32_bf16 v[76:79], v[154:157], v[178:181], v[76:79]
	v_mfma_f32_16x16x32_bf16 v[64:67], v[162:165], v[178:181], v[64:67]
	v_mfma_f32_16x16x32_bf16 v[60:63], v[154:157], v[186:189], v[60:63]
	v_mfma_f32_16x16x32_bf16 v[56:59], v[162:165], v[186:189], v[56:59]
	v_mfma_f32_16x16x32_bf16 v[48:51], v[154:157], v[194:197], v[48:51]
	v_mfma_f32_16x16x32_bf16 v[40:43], v[162:165], v[194:197], v[40:43]
	v_mfma_f32_16x16x32_bf16 v[36:39], v[154:157], v[202:205], v[36:39]
	v_mfma_f32_16x16x32_bf16 v[32:35], v[162:165], v[202:205], v[32:35]
	s_setprio 0
	s_barrier
	s_add_i32 s24, 0, 0x1c000
	s_add_i32 s25, s48, s27
	v_add_u32_e32 v218, s24, v168
	v_lshl_add_u64 v[150:151], v[150:151], 0, s[6:7]
	s_mov_b32 m0, s25
	ds_read_b128 v[206:209], v218
	ds_read_b128 v[210:213], v218 offset:1024
	ds_read_b128 v[214:217], v218 offset:2048
	ds_read_b128 v[218:221], v218 offset:3072
	global_load_lds_dwordx4 v[150:151], off
	v_lshl_add_u64 v[150:151], v[166:167], 0, s[6:7]
	s_add_i32 m0, s25, 0x2000
	s_nop 0
	global_load_lds_dwordx4 v[150:151], off
	s_barrier
	s_waitcnt lgkmcnt(0)
	s_setprio 1
	s_waitcnt lgkmcnt(0)
	v_mfma_f32_16x16x32_bf16 v[124:127], v[206:209], v[174:177], v[124:127]
	v_mfma_f32_16x16x32_bf16 v[120:123], v[214:217], v[174:177], v[120:123]
	v_mfma_f32_16x16x32_bf16 v[116:119], v[206:209], v[182:185], v[116:119]
	v_mfma_f32_16x16x32_bf16 v[112:115], v[214:217], v[182:185], v[112:115]
	v_mfma_f32_16x16x32_bf16 v[108:111], v[206:209], v[190:193], v[108:111]
	v_mfma_f32_16x16x32_bf16 v[104:107], v[214:217], v[190:193], v[104:107]
	v_mfma_f32_16x16x32_bf16 v[100:103], v[206:209], v[198:201], v[100:103]
	v_mfma_f32_16x16x32_bf16 v[96:99], v[214:217], v[198:201], v[96:99]
	v_mfma_f32_16x16x32_bf16 v[124:127], v[210:213], v[178:181], v[124:127]
	v_mfma_f32_16x16x32_bf16 v[120:123], v[218:221], v[178:181], v[120:123]
	v_mfma_f32_16x16x32_bf16 v[116:119], v[210:213], v[186:189], v[116:119]
	v_mfma_f32_16x16x32_bf16 v[112:115], v[218:221], v[186:189], v[112:115]
	v_mfma_f32_16x16x32_bf16 v[108:111], v[210:213], v[194:197], v[108:111]
	v_mfma_f32_16x16x32_bf16 v[104:107], v[218:221], v[194:197], v[104:107]
	v_mfma_f32_16x16x32_bf16 v[100:103], v[210:213], v[202:205], v[100:103]
	v_mfma_f32_16x16x32_bf16 v[96:99], v[218:221], v[202:205], v[96:99]
	s_setprio 0
	s_mov_b32 m0, s36
	v_lshl_add_u64 v[150:151], v[222:223], 0, s[6:7]
	s_barrier
	ds_read_b128 v[174:177], v171 offset:49152
	ds_read_b128 v[178:181], v171 offset:50176
	ds_read_b128 v[182:185], v171 offset:51200
	ds_read_b128 v[186:189], v171 offset:52224
	ds_read_b128 v[190:193], v171 offset:53248
	ds_read_b128 v[194:197], v171 offset:54272
	ds_read_b128 v[198:201], v171 offset:55296
	ds_read_b128 v[202:205], v171 offset:56320
	global_load_lds_dwordx4 v[150:151], off
	v_lshl_add_u64 v[150:151], v[224:225], 0, s[6:7]
	s_mov_b32 m0, s37
	s_nop 0
	global_load_lds_dwordx4 v[150:151], off
	s_barrier
	s_waitcnt lgkmcnt(0)
	s_setprio 1
	s_waitcnt lgkmcnt(0)
	v_mfma_f32_16x16x32_bf16 v[28:31], v[146:149], v[174:177], v[28:31]
	v_mfma_f32_16x16x32_bf16 v[24:27], v[158:161], v[174:177], v[24:27]
	v_mfma_f32_16x16x32_bf16 v[20:23], v[146:149], v[182:185], v[20:23]
	v_mfma_f32_16x16x32_bf16 v[16:19], v[158:161], v[182:185], v[16:19]
	v_mfma_f32_16x16x32_bf16 v[12:15], v[146:149], v[190:193], v[12:15]
	v_mfma_f32_16x16x32_bf16 v[8:11], v[158:161], v[190:193], v[8:11]
	v_mfma_f32_16x16x32_bf16 v[4:7], v[146:149], v[198:201], v[4:7]
	v_mfma_f32_16x16x32_bf16 v[0:3], v[158:161], v[198:201], v[0:3]
	v_mfma_f32_16x16x32_bf16 v[28:31], v[154:157], v[178:181], v[28:31]
	v_mfma_f32_16x16x32_bf16 v[24:27], v[162:165], v[178:181], v[24:27]
	v_mfma_f32_16x16x32_bf16 v[20:23], v[154:157], v[186:189], v[20:23]
	v_mfma_f32_16x16x32_bf16 v[16:19], v[162:165], v[186:189], v[16:19]
	v_mfma_f32_16x16x32_bf16 v[12:15], v[154:157], v[194:197], v[12:15]
	v_mfma_f32_16x16x32_bf16 v[8:11], v[162:165], v[194:197], v[8:11]
	v_mfma_f32_16x16x32_bf16 v[4:7], v[154:157], v[202:205], v[4:7]
	v_mfma_f32_16x16x32_bf16 v[0:3], v[162:165], v[202:205], v[0:3]
	s_setprio 0
	s_barrier
	s_add_u32 s22, s22, 0x40080
	s_addc_u32 s23, s23, 0
	s_add_i32 s24, s24, s27
	v_lshl_add_u64 v[146:147], s[22:23], 0, v[132:133]
	s_mov_b32 m0, s24
	s_nop 0
	global_load_lds_dwordx4 v[146:147], off
	v_lshl_add_u64 v[146:147], s[22:23], 0, v[128:129]
	s_add_i32 m0, s24, 0x2000
	s_nop 0
	global_load_lds_dwordx4 v[146:147], off
	s_waitcnt vmcnt(6)
	s_barrier
; __device__ __forceinline__ unsigned pk2(float lo, float hi) { const f32x2 v = (f32x2){lo, hi}; const bf16x2_t b = __builtin_convertvector(v, bf16x2_t); return __builtin_bit_cast(unsigned, b); }
;     __device__ __forceinline__ void operator()(const f32x4 (&acc)[2][2][4][2], const Unit& u, int wr, int wc, int fr, int fq, const float (&)[8]) const {
;     ...
;         if (DT && u.pn == 20) {
;             if (wc == 0) {
; #pragma unroll
;                 for (int ai = 0; ai < 2; ++ai)
; #pragma unroll
;                     for (int m = 0; m < 4; ++m) { const int row = row0 + ai * HALF + m * 16; const float rs = rsqrtf(ep[ai * 4 + m] * (1.0f / 1024.0f) + EPS);
;                         *(f32x4*)(dt + (size_t)row * 32 + 8 * fq) = acc[ai][0][m][0] * rs; *(f32x4*)(dt + (size_t)row * 32 + 8 * fq + 4) = acc[ai][0][m][1] * rs; }
;             }
;             return;
;         }
;         const int col0 = u.pn * BM + wc * 32 + 8 * fq;
; #pragma unroll
;         for (int ai = 0; ai < 2; ++ai)
; #pragma unroll
;             for (int m = 0; m < 4; ++m) { const int row = row0 + ai * HALF + m * 16; const float rs = rsqrtf(ep[ai * 4 + m] * (1.0f / 1024.0f) + EPS);
;                 u16* rowp = O + (size_t)row * ldc + col0;
; #pragma unroll
;                 for (int bj = 0; bj < 2; ++bj) { f32x4 v0 = acc[ai][bj][m][0] * rs, v1 = acc[ai][bj][m][1] * rs;
;                     if (ACT == 1) {
; #pragma unroll
;                         for (int j = 0; j < 4; ++j) { const float a0 = fmaxf(v0[j], 0.f), a1 = fmaxf(v1[j], 0.f); v0[j] = a0 * a0; v1[j] = a1 * a1; } }
;                     u32x4 w; w.x = pk2(v0[0], v0[1]); w.y = pk2(v0[2], v0[3]); w.z = pk2(v1[0], v1[1]); w.w = pk2(v1[2], v1[3]);
;                     *(u32x4*)(rowp + bj * HALF) = w; } }
	s_setprio 1
	v_mfma_f32_16x16x32_bf16 v[92:95], v[206:209], v[174:177], v[92:95]
	v_mfma_f32_16x16x32_bf16 v[88:91], v[214:217], v[174:177], v[88:91]
	v_mfma_f32_16x16x32_bf16 v[84:87], v[206:209], v[182:185], v[84:87]
	v_mfma_f32_16x16x32_bf16 v[80:83], v[214:217], v[182:185], v[80:83]
	v_mfma_f32_16x16x32_bf16 v[72:75], v[206:209], v[190:193], v[72:75]
	v_mfma_f32_16x16x32_bf16 v[68:71], v[214:217], v[190:193], v[68:71]
	v_mfma_f32_16x16x32_bf16 v[52:55], v[206:209], v[198:201], v[52:55]
	v_mfma_f32_16x16x32_bf16 v[44:47], v[214:217], v[198:201], v[44:47]
	v_mfma_f32_16x16x32_bf16 v[92:95], v[210:213], v[178:181], v[92:95]
	v_mfma_f32_16x16x32_bf16 v[88:91], v[218:221], v[178:181], v[88:91]
	v_mfma_f32_16x16x32_bf16 v[84:87], v[210:213], v[186:189], v[84:87]
	v_mfma_f32_16x16x32_bf16 v[80:83], v[218:221], v[186:189], v[80:83]
	v_mfma_f32_16x16x32_bf16 v[72:75], v[210:213], v[194:197], v[72:75]
	v_mfma_f32_16x16x32_bf16 v[68:71], v[218:221], v[194:197], v[68:71]
	v_mfma_f32_16x16x32_bf16 v[52:55], v[210:213], v[202:205], v[52:55]
	v_mfma_f32_16x16x32_bf16 v[44:47], v[218:221], v[202:205], v[44:47]
	s_setprio 0
	s_add_i32 s47, s47, 2
	s_add_u32 s20, s20, 0x100
	s_addc_u32 s21, s21, 0
	s_add_u32 s45, s45, 0x100
	s_addc_u32 s46, s46, 0
	s_cmp_gt_u32 s47, 13
	s_barrier
	s_cbranch_scc0 .LBB0_205
	s_bfe_u32 vcc_lo, s18, 0x20003
	s_lshl_b32 vcc_lo, vcc_lo, 10
	s_add_i32 vcc_lo, vcc_lo, 0x20010
	v_lshl_add_u32 v236, v153, 2, vcc_lo
	ds_read_b32 v228, v236
	ds_read_b32 v229, v236 offset:64
	ds_read_b32 v230, v236 offset:128
	ds_read_b32 v231, v236 offset:192
	ds_read_b32 v232, v236 offset:512
	ds_read_b32 v233, v236 offset:576
	ds_read_b32 v234, v236 offset:640
	ds_read_b32 v235, v236 offset:704
	s_waitcnt lgkmcnt(0)
	v_lshl_add_u32 v162, s18, 8, v153
	v_ashrrev_i32_e32 v163, 31, v162
	v_or_b32_e32 v160, 16, v162
	v_or_b32_e32 v158, 32, v162
	v_or_b32_e32 v156, 48, v162
	v_ashrrev_i32_e32 v161, 31, v160
	v_ashrrev_i32_e32 v159, 31, v158
	v_ashrrev_i32_e32 v157, 31, v156
	v_add_u32_e32 v154, 0x80, v162
	v_add_u32_e32 v150, 0x90, v162
	v_add_u32_e32 v148, 0xa0, v162
	v_add_u32_e32 v146, 0xb0, v162
	v_ashrrev_i32_e32 v155, 31, v154
	v_ashrrev_i32_e32 v151, 31, v150
	v_ashrrev_i32_e32 v149, 31, v148
	v_ashrrev_i32_e32 v147, 31, v146
	s_cmp_lg_u32 s43, 20
	s_mov_b64 s[18:19], -1
	s_cbranch_scc0 .LBB0_208
	s_waitcnt vmcnt(8)
	v_lshl_or_b32 v166, s43, 8, v169
	v_ashrrev_i32_e32 v167, 31, v166
	v_lshlrev_b64 v[166:167], 1, v[166:167]
	v_mov_b32_e32 v186, v228
	v_mov_b64_e32 v[164:165], s[96:97]
	v_mad_i64_i32 v[182:183], s[18:19], v162, s42, v[164:165]
	v_lshl_add_u64 v[188:189], v[182:183], 0, v[166:167]
	v_pk_mul_f32 v[184:185], v[78:79], v[186:187] op_sel_hi:[1,0]
	v_pk_mul_f32 v[182:183], v[76:77], v[186:187] op_sel_hi:[1,0]
	v_pk_mul_f32 v[190:191], v[66:67], v[186:187] op_sel_hi:[1,0]
	v_pk_mul_f32 v[192:193], v[64:65], v[186:187] op_sel_hi:[1,0]
	v_cvt_pk_bf16_f32 v182, v182, v183
	v_cvt_pk_bf16_f32 v183, v184, v185
	v_cvt_pk_bf16_f32 v184, v192, v193
	v_cvt_pk_bf16_f32 v185, v190, v191
	v_pk_mul_f32 v[124:125], v[124:125], v[186:187] op_sel_hi:[1,0]
	global_store_dwordx4 v[188:189], v[182:185], off
	v_pk_mul_f32 v[126:127], v[126:127], v[186:187] op_sel_hi:[1,0]
	s_nop 0
	v_pk_mul_f32 v[182:183], v[122:123], v[186:187] op_sel_hi:[1,0]
	v_pk_mul_f32 v[122:123], v[120:121], v[186:187] op_sel_hi:[1,0]
	v_cvt_pk_bf16_f32 v120, v124, v125
	v_cvt_pk_bf16_f32 v121, v126, v127
	v_cvt_pk_bf16_f32 v122, v122, v123
	v_cvt_pk_bf16_f32 v123, v182, v183
	global_store_dwordx4 v[188:189], v[120:123], off offset:256
	s_nop 1
	v_mov_b32_e32 v124, v229
	v_mad_i64_i32 v[120:121], s[18:19], v160, s42, v[164:165]
	v_lshl_add_u64 v[126:127], v[120:121], 0, v[166:167]
	v_pk_mul_f32 v[122:123], v[62:63], v[124:125] op_sel_hi:[1,0]
	v_pk_mul_f32 v[120:121], v[60:61], v[124:125] op_sel_hi:[1,0]
	v_pk_mul_f32 v[182:183], v[58:59], v[124:125] op_sel_hi:[1,0]
	v_pk_mul_f32 v[184:185], v[56:57], v[124:125] op_sel_hi:[1,0]
	v_cvt_pk_bf16_f32 v120, v120, v121
	v_cvt_pk_bf16_f32 v121, v122, v123
	v_cvt_pk_bf16_f32 v122, v184, v185
	v_cvt_pk_bf16_f32 v123, v182, v183
	v_pk_mul_f32 v[116:117], v[116:117], v[124:125] op_sel_hi:[1,0]
	global_store_dwordx4 v[126:127], v[120:123], off
	v_pk_mul_f32 v[118:119], v[118:119], v[124:125] op_sel_hi:[1,0]
	s_nop 0
	v_pk_mul_f32 v[120:121], v[114:115], v[124:125] op_sel_hi:[1,0]
	v_pk_mul_f32 v[114:115], v[112:113], v[124:125] op_sel_hi:[1,0]
	v_cvt_pk_bf16_f32 v112, v116, v117
	v_cvt_pk_bf16_f32 v113, v118, v119
	v_cvt_pk_bf16_f32 v114, v114, v115
	v_cvt_pk_bf16_f32 v115, v120, v121
	global_store_dwordx4 v[126:127], v[112:115], off offset:256
	s_nop 1
	v_mov_b32_e32 v116, v230
	v_mad_i64_i32 v[112:113], s[18:19], v158, s42, v[164:165]
	v_lshl_add_u64 v[118:119], v[112:113], 0, v[166:167]
	v_pk_mul_f32 v[114:115], v[50:51], v[116:117] op_sel_hi:[1,0]
	v_pk_mul_f32 v[112:113], v[48:49], v[116:117] op_sel_hi:[1,0]
	v_pk_mul_f32 v[120:121], v[42:43], v[116:117] op_sel_hi:[1,0]
	v_pk_mul_f32 v[122:123], v[40:41], v[116:117] op_sel_hi:[1,0]
	v_cvt_pk_bf16_f32 v112, v112, v113
	v_cvt_pk_bf16_f32 v113, v114, v115
	v_cvt_pk_bf16_f32 v114, v122, v123
	v_cvt_pk_bf16_f32 v115, v120, v121
	v_pk_mul_f32 v[108:109], v[108:109], v[116:117] op_sel_hi:[1,0]
	global_store_dwordx4 v[118:119], v[112:115], off
	v_pk_mul_f32 v[110:111], v[110:111], v[116:117] op_sel_hi:[1,0]
	s_nop 0
; __device__ __forceinline__ unsigned pk2(float lo, float hi) { const f32x2 v = (f32x2){lo, hi}; const bf16x2_t b = __builtin_convertvector(v, bf16x2_t); return __builtin_bit_cast(unsigned, b); }
;     __device__ __forceinline__ void operator()(const f32x4 (&acc)[2][2][4][2], const Unit& u, int wr, int wc, int fr, int fq, const float (&)[8]) const {
;     ...
;         const int col0 = u.pn * BM + wc * 32 + 8 * fq;
; #pragma unroll
;         for (int ai = 0; ai < 2; ++ai)
; #pragma unroll
;             for (int m = 0; m < 4; ++m) { const int row = row0 + ai * HALF + m * 16; const float rs = rsqrtf(ep[ai * 4 + m] * (1.0f / 1024.0f) + EPS);
;                 u16* rowp = O + (size_t)row * ldc + col0;
; #pragma unroll
;                 for (int bj = 0; bj < 2; ++bj) { f32x4 v0 = acc[ai][bj][m][0] * rs, v1 = acc[ai][bj][m][1] * rs;
;                     if (ACT == 1) {
; #pragma unroll
;                         for (int j = 0; j < 4; ++j) { const float a0 = fmaxf(v0[j], 0.f), a1 = fmaxf(v1[j], 0.f); v0[j] = a0 * a0; v1[j] = a1 * a1; } }
;                     u32x4 w; w.x = pk2(v0[0], v0[1]); w.y = pk2(v0[2], v0[3]); w.z = pk2(v1[0], v1[1]); w.w = pk2(v1[2], v1[3]);
;                     *(u32x4*)(rowp + bj * HALF) = w; } }
	v_pk_mul_f32 v[112:113], v[106:107], v[116:117] op_sel_hi:[1,0]
	v_pk_mul_f32 v[106:107], v[104:105], v[116:117] op_sel_hi:[1,0]
	v_cvt_pk_bf16_f32 v104, v108, v109
	v_cvt_pk_bf16_f32 v105, v110, v111
	v_cvt_pk_bf16_f32 v106, v106, v107
	v_cvt_pk_bf16_f32 v107, v112, v113
	global_store_dwordx4 v[118:119], v[104:107], off offset:256
	s_nop 1
	v_mov_b32_e32 v108, v231
	v_mad_i64_i32 v[104:105], s[18:19], v156, s42, v[164:165]
	v_lshl_add_u64 v[110:111], v[104:105], 0, v[166:167]
	v_pk_mul_f32 v[106:107], v[38:39], v[108:109] op_sel_hi:[1,0]
	v_pk_mul_f32 v[104:105], v[36:37], v[108:109] op_sel_hi:[1,0]
	v_pk_mul_f32 v[112:113], v[34:35], v[108:109] op_sel_hi:[1,0]
	v_pk_mul_f32 v[114:115], v[32:33], v[108:109] op_sel_hi:[1,0]
	v_cvt_pk_bf16_f32 v104, v104, v105
	v_cvt_pk_bf16_f32 v105, v106, v107
	v_cvt_pk_bf16_f32 v106, v114, v115
	v_cvt_pk_bf16_f32 v107, v112, v113
	v_pk_mul_f32 v[100:101], v[100:101], v[108:109] op_sel_hi:[1,0]
	global_store_dwordx4 v[110:111], v[104:107], off
	v_pk_mul_f32 v[102:103], v[102:103], v[108:109] op_sel_hi:[1,0]
	s_nop 0
	v_pk_mul_f32 v[104:105], v[98:99], v[108:109] op_sel_hi:[1,0]
	v_pk_mul_f32 v[98:99], v[96:97], v[108:109] op_sel_hi:[1,0]
	v_cvt_pk_bf16_f32 v96, v100, v101
	v_cvt_pk_bf16_f32 v97, v102, v103
	v_cvt_pk_bf16_f32 v98, v98, v99
	v_cvt_pk_bf16_f32 v99, v104, v105
	global_store_dwordx4 v[110:111], v[96:99], off offset:256
	s_nop 1
	v_mov_b32_e32 v100, v232
	v_mad_i64_i32 v[96:97], s[18:19], v154, s42, v[164:165]
	v_lshl_add_u64 v[102:103], v[96:97], 0, v[166:167]
	v_pk_mul_f32 v[98:99], v[30:31], v[100:101] op_sel_hi:[1,0]
	v_pk_mul_f32 v[96:97], v[28:29], v[100:101] op_sel_hi:[1,0]
	v_pk_mul_f32 v[104:105], v[26:27], v[100:101] op_sel_hi:[1,0]
	v_pk_mul_f32 v[106:107], v[24:25], v[100:101] op_sel_hi:[1,0]
	v_cvt_pk_bf16_f32 v96, v96, v97
	v_cvt_pk_bf16_f32 v97, v98, v99
	v_cvt_pk_bf16_f32 v98, v106, v107
	v_cvt_pk_bf16_f32 v99, v104, v105
	v_pk_mul_f32 v[92:93], v[92:93], v[100:101] op_sel_hi:[1,0]
	global_store_dwordx4 v[102:103], v[96:99], off
	v_pk_mul_f32 v[94:95], v[94:95], v[100:101] op_sel_hi:[1,0]
	s_nop 0
	v_pk_mul_f32 v[96:97], v[90:91], v[100:101] op_sel_hi:[1,0]
	v_pk_mul_f32 v[90:91], v[88:89], v[100:101] op_sel_hi:[1,0]
	v_cvt_pk_bf16_f32 v88, v92, v93
	v_cvt_pk_bf16_f32 v89, v94, v95
	v_cvt_pk_bf16_f32 v90, v90, v91
	v_cvt_pk_bf16_f32 v91, v96, v97
	global_store_dwordx4 v[102:103], v[88:91], off offset:256
	s_nop 1
	v_mov_b32_e32 v92, v233
	v_mad_i64_i32 v[88:89], s[18:19], v150, s42, v[164:165]
	v_lshl_add_u64 v[94:95], v[88:89], 0, v[166:167]
	v_pk_mul_f32 v[90:91], v[22:23], v[92:93] op_sel_hi:[1,0]
	v_pk_mul_f32 v[88:89], v[20:21], v[92:93] op_sel_hi:[1,0]
	v_pk_mul_f32 v[96:97], v[18:19], v[92:93] op_sel_hi:[1,0]
	v_pk_mul_f32 v[98:99], v[16:17], v[92:93] op_sel_hi:[1,0]
	v_cvt_pk_bf16_f32 v88, v88, v89
	v_cvt_pk_bf16_f32 v89, v90, v91
	v_cvt_pk_bf16_f32 v90, v98, v99
	v_cvt_pk_bf16_f32 v91, v96, v97
	v_pk_mul_f32 v[84:85], v[84:85], v[92:93] op_sel_hi:[1,0]
	global_store_dwordx4 v[94:95], v[88:91], off
	v_pk_mul_f32 v[86:87], v[86:87], v[92:93] op_sel_hi:[1,0]
	s_nop 0
	v_pk_mul_f32 v[88:89], v[82:83], v[92:93] op_sel_hi:[1,0]
	v_pk_mul_f32 v[82:83], v[80:81], v[92:93] op_sel_hi:[1,0]
	v_cvt_pk_bf16_f32 v80, v84, v85
	v_cvt_pk_bf16_f32 v81, v86, v87
	v_cvt_pk_bf16_f32 v82, v82, v83
	v_cvt_pk_bf16_f32 v83, v88, v89
	global_store_dwordx4 v[94:95], v[80:83], off offset:256
	s_nop 1
	v_mov_b32_e32 v84, v234
	v_mad_i64_i32 v[80:81], s[18:19], v148, s42, v[164:165]
	v_lshl_add_u64 v[86:87], v[80:81], 0, v[166:167]
	v_pk_mul_f32 v[82:83], v[14:15], v[84:85] op_sel_hi:[1,0]
	v_pk_mul_f32 v[80:81], v[12:13], v[84:85] op_sel_hi:[1,0]
	v_pk_mul_f32 v[88:89], v[10:11], v[84:85] op_sel_hi:[1,0]
	v_pk_mul_f32 v[90:91], v[8:9], v[84:85] op_sel_hi:[1,0]
	v_cvt_pk_bf16_f32 v80, v80, v81
	v_cvt_pk_bf16_f32 v81, v82, v83
	v_cvt_pk_bf16_f32 v82, v90, v91
	v_cvt_pk_bf16_f32 v83, v88, v89
	v_pk_mul_f32 v[72:73], v[72:73], v[84:85] op_sel_hi:[1,0]
	global_store_dwordx4 v[86:87], v[80:83], off
	v_pk_mul_f32 v[74:75], v[74:75], v[84:85] op_sel_hi:[1,0]
	s_nop 0
	v_pk_mul_f32 v[80:81], v[70:71], v[84:85] op_sel_hi:[1,0]
	v_pk_mul_f32 v[70:71], v[68:69], v[84:85] op_sel_hi:[1,0]
	v_cvt_pk_bf16_f32 v68, v72, v73
	v_cvt_pk_bf16_f32 v69, v74, v75
	v_cvt_pk_bf16_f32 v70, v70, v71
	v_cvt_pk_bf16_f32 v71, v80, v81
	global_store_dwordx4 v[86:87], v[68:71], off offset:256
	s_nop 1
	v_mov_b32_e32 v72, v235
	v_mad_i64_i32 v[68:69], s[18:19], v146, s42, v[164:165]
	v_lshl_add_u64 v[74:75], v[68:69], 0, v[166:167]
	v_pk_mul_f32 v[70:71], v[6:7], v[72:73] op_sel_hi:[1,0]
	v_pk_mul_f32 v[68:69], v[4:5], v[72:73] op_sel_hi:[1,0]
	v_pk_mul_f32 v[80:81], v[2:3], v[72:73] op_sel_hi:[1,0]
	v_pk_mul_f32 v[82:83], v[0:1], v[72:73] op_sel_hi:[1,0]
	v_cvt_pk_bf16_f32 v68, v68, v69
	v_cvt_pk_bf16_f32 v69, v70, v71
	v_cvt_pk_bf16_f32 v70, v82, v83
	v_cvt_pk_bf16_f32 v71, v80, v81
	global_store_dwordx4 v[74:75], v[68:71], off
	v_pk_mul_f32 v[54:55], v[54:55], v[72:73] op_sel_hi:[1,0]
	v_pk_mul_f32 v[52:53], v[52:53], v[72:73] op_sel_hi:[1,0]
	v_pk_mul_f32 v[68:69], v[46:47], v[72:73] op_sel_hi:[1,0]
	v_pk_mul_f32 v[46:47], v[44:45], v[72:73] op_sel_hi:[1,0]
	v_cvt_pk_bf16_f32 v44, v52, v53
	v_cvt_pk_bf16_f32 v45, v54, v55
	v_cvt_pk_bf16_f32 v46, v46, v47
	v_cvt_pk_bf16_f32 v47, v68, v69
	global_store_dwordx4 v[74:75], v[44:47], off offset:256
	s_mov_b64 s[18:19], 0

; __device__ __forceinline__ void ssd_phase(const Args& A, unsigned char* smem, const bool dry) {
;     ...
;             const float a_neg = -__expf(A.in[4][dir * 16 + h]); const float dtb = A.in[5][dir * 16 + h];
;             f32x4 Sacc[4];
; #pragma unroll
;             for (int j = 0; j < 4; ++j) Sacc[j] = (f32x4){0.f, 0.f, 0.f, 0.f};
;             __syncthreads();
;             for (int e = tid; e < 64 * 136 / 2; e += 512) ((unsigned*)Sb)[e] = 0u;
;             u32x4 pre[5]; float dpre = 0.f;
;     ...
;             SSD_ISSUE(0);
.LBB0_427:
	s_or_b64 exec, exec, s[18:19]
	s_waitcnt vmcnt(6)
	v_mul_f32_e32 v21, 0x3fb8aa3b, v21
	v_exp_f32_e32 v168, v21
	v_lshl_add_u64 v[68:69], v[22:23], 2, s[44:45]
	s_mov_b32 s22, 0
	s_mov_b32 s23, 0
	s_mov_b32 s26, 0
	v_mov_b32_e32 v21, v20
	v_mov_b32_e32 v22, v20
	v_mov_b32_e32 v23, v20
	v_mov_b32_e32 v24, v20
	v_mov_b32_e32 v25, v20
	v_mov_b32_e32 v26, v20
	v_mov_b32_e32 v27, v20
	v_mov_b32_e32 v28, v20
	v_mov_b32_e32 v29, v20
	v_mov_b32_e32 v30, v20
	v_mov_b32_e32 v31, v20
	v_mov_b32_e32 v32, v20
	v_mov_b32_e32 v33, v20
	v_mov_b32_e32 v34, v20
	v_mov_b32_e32 v35, v20
	s_waitcnt vmcnt(0)
	s_branch .LBB0_429

; __device__ __forceinline__ void ssd_phase(const Args& A, unsigned char* smem, const bool dry) {
;     ...
;                 for (int k = 0; k < 5; ++k) { const int it_ = tid + 512 * k; const int o = it_ % 40, i = it_ / 40;
;                     if (o < 8) *(u32x4*)(Xb + i * 72 + 8 * o) = pre[k];
;                     else if (o < 24) *(u32x4*)(Bb + i * 136 + 8 * (o - 8)) = pre[k];
;                     else *(u32x4*)(Cb + i * 136 + 8 * (o - 24)) = pre[k]; }
.LBB0_440:
	s_and_saveexec_b64 s[18:19], s[12:13]
	s_xor_b64 s[18:19], exec, s[18:19]
	s_cbranch_execz .LBB0_442
	s_waitcnt vmcnt(5)
	ds_write_b128 v117, v[0:3]
.LBB0_442:
	s_andn2_saveexec_b64 s[18:19], s[18:19]
	s_cbranch_execz .LBB0_444
	s_waitcnt vmcnt(5)
	ds_write_b128 v116, v[0:3] offset:17280

; __device__ __forceinline__ void ssd_phase(const Args& A, unsigned char* smem, const bool dry) {
;     ...
;                 for (int k = 0; k < 5; ++k) { const int it_ = tid + 512 * k; const int o = it_ % 40, i = it_ / 40;
;                     if (o < 8) *(u32x4*)(Xb + i * 72 + 8 * o) = pre[k];
;                     else if (o < 24) *(u32x4*)(Bb + i * 136 + 8 * (o - 8)) = pre[k];
;                     else *(u32x4*)(Cb + i * 136 + 8 * (o - 24)) = pre[k]; }
.LBB0_445:
	s_waitcnt lgkmcnt(0)
	v_add3_u32 v36, s7, v118, v115
	s_waitcnt vmcnt(5)
	ds_write_b128 v36, v[0:3] offset:52224
	s_or_b64 exec, exec, s[14:15]
	s_and_saveexec_b64 s[14:15], s[16:17]
	s_xor_b64 s[14:15], exec, s[14:15]
	s_cbranch_execz .LBB0_432
.LBB0_446:
	s_and_saveexec_b64 s[18:19], s[20:21]
	s_xor_b64 s[18:19], exec, s[18:19]
	s_cbranch_execz .LBB0_448
	s_waitcnt vmcnt(4)
	ds_write_b128 v121, v[4:7]
.LBB0_448:
	s_andn2_saveexec_b64 s[18:19], s[18:19]
	s_cbranch_execz .LBB0_450
	s_waitcnt vmcnt(4)
	ds_write_b128 v120, v[4:7] offset:17280

; __device__ __forceinline__ void ssd_phase(const Args& A, unsigned char* smem, const bool dry) {
;     ...
;                 for (int k = 0; k < 5; ++k) { const int it_ = tid + 512 * k; const int o = it_ % 40, i = it_ / 40;
;                     if (o < 8) *(u32x4*)(Xb + i * 72 + 8 * o) = pre[k];
;                     else if (o < 24) *(u32x4*)(Bb + i * 136 + 8 * (o - 8)) = pre[k];
;                     else *(u32x4*)(Cb + i * 136 + 8 * (o - 24)) = pre[k]; }
.LBB0_451:
	s_waitcnt lgkmcnt(0)
	v_add3_u32 v36, s7, v122, v119
	s_waitcnt vmcnt(4)
	ds_write_b128 v36, v[4:7] offset:52224
	s_or_b64 exec, exec, s[14:15]
	s_and_saveexec_b64 s[14:15], s[24:25]
	s_xor_b64 s[14:15], exec, s[14:15]
	s_cbranch_execz .LBB0_434
.LBB0_452:
	s_and_saveexec_b64 s[18:19], s[28:29]
	s_xor_b64 s[18:19], exec, s[18:19]
	s_cbranch_execz .LBB0_454
	s_waitcnt vmcnt(3)
	ds_write_b128 v125, v[8:11]
.LBB0_454:
	s_andn2_saveexec_b64 s[18:19], s[18:19]
	s_cbranch_execz .LBB0_456
	s_waitcnt vmcnt(3)
	ds_write_b128 v124, v[8:11] offset:17280

; __device__ __forceinline__ void ssd_phase(const Args& A, unsigned char* smem, const bool dry) {
;     ...
;                 for (int k = 0; k < 5; ++k) { const int it_ = tid + 512 * k; const int o = it_ % 40, i = it_ / 40;
;                     if (o < 8) *(u32x4*)(Xb + i * 72 + 8 * o) = pre[k];
;                     else if (o < 24) *(u32x4*)(Bb + i * 136 + 8 * (o - 8)) = pre[k];
;                     else *(u32x4*)(Cb + i * 136 + 8 * (o - 24)) = pre[k]; }
.LBB0_457:
	s_waitcnt lgkmcnt(0)
	v_add3_u32 v36, s7, v126, v123
	s_waitcnt vmcnt(3)
	ds_write_b128 v36, v[8:11] offset:52224
	s_or_b64 exec, exec, s[14:15]
	s_and_saveexec_b64 s[14:15], s[34:35]
	s_xor_b64 s[14:15], exec, s[14:15]
	s_cbranch_execz .LBB0_436
.LBB0_458:
	s_and_saveexec_b64 s[18:19], s[38:39]
	s_xor_b64 s[18:19], exec, s[18:19]
	s_cbranch_execz .LBB0_460
	s_waitcnt vmcnt(2)
	ds_write_b128 v129, v[12:15]
.LBB0_460:
	s_andn2_saveexec_b64 s[18:19], s[18:19]
	s_cbranch_execz .LBB0_462
	s_waitcnt vmcnt(2)
	ds_write_b128 v128, v[12:15] offset:17280

; __device__ __forceinline__ void ssd_phase(const Args& A, unsigned char* smem, const bool dry) {
;     ...
;                 for (int k = 0; k < 5; ++k) { const int it_ = tid + 512 * k; const int o = it_ % 40, i = it_ / 40;
;                     if (o < 8) *(u32x4*)(Xb + i * 72 + 8 * o) = pre[k];
;                     else if (o < 24) *(u32x4*)(Bb + i * 136 + 8 * (o - 8)) = pre[k];
;                     else *(u32x4*)(Cb + i * 136 + 8 * (o - 24)) = pre[k]; }
.LBB0_463:
	s_waitcnt lgkmcnt(0)
	v_add3_u32 v36, s7, v130, v127
	s_waitcnt vmcnt(2)
	ds_write_b128 v36, v[12:15] offset:52224
	s_or_b64 exec, exec, s[14:15]
	s_and_saveexec_b64 s[14:15], s[42:43]
	s_xor_b64 s[14:15], exec, s[14:15]
	s_cbranch_execz .LBB0_438
.LBB0_464:
	s_and_saveexec_b64 s[18:19], s[46:47]
	s_xor_b64 s[18:19], exec, s[18:19]
	s_cbranch_execz .LBB0_466
	s_waitcnt vmcnt(1)
	ds_write_b128 v133, v[16:19]
.LBB0_466:
	s_andn2_saveexec_b64 s[18:19], s[18:19]
	s_cbranch_execz .LBB0_468
	s_waitcnt vmcnt(1)
	ds_write_b128 v132, v[16:19] offset:17280

; __device__ __forceinline__ void ssd_phase(const Args& A, unsigned char* smem, const bool dry) {
;     ...
;                 for (int k = 0; k < 5; ++k) { const int it_ = tid + 512 * k; const int o = it_ % 40, i = it_ / 40;
;                     if (o < 8) *(u32x4*)(Xb + i * 72 + 8 * o) = pre[k];
;                     else if (o < 24) *(u32x4*)(Bb + i * 136 + 8 * (o - 8)) = pre[k];
;                     else *(u32x4*)(Cb + i * 136 + 8 * (o - 24)) = pre[k]; }
;                 if (tid < 64) {
;                     const float v = dpre + dtb; const float dt = v > 20.f ? v : log1pf(__expf(v));
;                     float c = dt * a_neg;
; #pragma unroll
;                     for (int d = 1; d < 64; d <<= 1) { const float tv = __shfl_up(c, d); if (lane >= d) c += tv; }
;                     const float tot = __shfl(c, 63);
;                     cumv[lane] = c; dtv[lane] = dt; wv[lane] = dt * __expf(tot - c); ecv[lane] = __expf(c); if (lane == 0) etot[0] = __expf(tot); }
.LBB0_469:
	s_waitcnt lgkmcnt(0)
	v_add3_u32 v36, s7, v134, v131
	s_waitcnt vmcnt(1)
	ds_write_b128 v36, v[16:19] offset:52224
	s_or_b64 exec, exec, s[14:15]
	s_and_saveexec_b64 s[74:75], s[0:1]
	s_cbranch_execz .LBB0_474
.LBB0_470:
	s_waitcnt vmcnt(1) lgkmcnt(0)
	v_add_f32_e32 v36, v166, v167
	s_mov_b32 s14, 0x41a00000
	v_cmp_nlt_f32_e32 vcc, s14, v36
	s_and_saveexec_b64 s[14:15], vcc
	s_cbranch_execz .LBB0_472
	v_mul_f32_e32 v36, 0x3fb8aa3b, v36
	v_exp_f32_e32 v46, v36
	s_mov_b32 s18, 0x3f2aaaab
	v_add_f32_e32 v38, 1.0, v46
	v_frexp_mant_f32_e32 v40, v38
	v_cvt_f64_f32_e32 v[36:37], v38
	v_frexp_exp_i32_f64_e32 v36, v[36:37]
	v_cmp_gt_f32_e32 vcc, s18, v40
	v_add_f32_e32 v39, -1.0, v38
	v_sub_f32_e32 v41, v39, v38
	v_subbrev_co_u32_e32 v70, vcc, 0, v36, vcc
	v_sub_u32_e32 v36, 0, v70
	v_sub_f32_e32 v39, v46, v39
	v_add_f32_e32 v41, 1.0, v41
	v_ldexp_f32 v37, v38, v36
	v_add_f32_e32 v39, v39, v41
	v_add_f32_e32 v38, -1.0, v37
	v_add_f32_e32 v40, 1.0, v37
	v_ldexp_f32 v36, v39, v36
	v_add_f32_e32 v39, 1.0, v38
	v_add_f32_e32 v41, -1.0, v40
	v_sub_f32_e32 v39, v37, v39
	v_sub_f32_e32 v37, v37, v41
	v_add_f32_e32 v39, v36, v39
	v_add_f32_e32 v36, v36, v37
	v_add_f32_e32 v53, v40, v36
	v_rcp_f32_e32 v72, v53
	v_sub_f32_e32 v37, v53, v40
	v_sub_f32_e32 v71, v36, v37
	v_add_f32_e32 v37, v38, v39
	v_mul_f32_e32 v74, v37, v72
	v_sub_f32_e32 v36, v37, v38
	v_mul_f32_e32 v38, v53, v74
	v_fma_f32 v40, v74, v53, -v38
	v_fmac_f32_e32 v40, v74, v71
	v_sub_f32_e32 v73, v39, v36
	v_add_f32_e32 v36, v38, v40
	v_sub_f32_e32 v39, v37, v36
	v_pk_add_f32 v[42:43], v[36:37], v[38:39] neg_lo:[0,1] neg_hi:[0,1]
	v_mov_b32_e32 v41, v36
	v_pk_add_f32 v[36:37], v[42:43], v[40:41] neg_lo:[0,1] neg_hi:[0,1]
	s_mov_b32 s18, 0x3f317218
	v_add_f32_e32 v37, v73, v37
	v_add_f32_e32 v36, v36, v37
	v_add_f32_e32 v37, v39, v36
	v_mul_f32_e32 v73, v72, v37
	v_mul_f32_e32 v38, v53, v73
	v_fma_f32 v40, v73, v53, -v38
	v_fmac_f32_e32 v40, v73, v71
	v_sub_f32_e32 v39, v39, v37
	v_add_f32_e32 v53, v36, v39
	v_add_f32_e32 v36, v38, v40
	v_sub_f32_e32 v39, v37, v36
	v_pk_add_f32 v[42:43], v[36:37], v[38:39] neg_lo:[0,1] neg_hi:[0,1]
	v_mov_b32_e32 v41, v36
	v_pk_add_f32 v[36:37], v[42:43], v[40:41] neg_lo:[0,1] neg_hi:[0,1]
	s_nop 0
	v_add_f32_e32 v37, v53, v37
	v_add_f32_e32 v36, v36, v37
	v_add_f32_e32 v37, v74, v73
	v_add_f32_e32 v36, v39, v36
	v_sub_f32_e32 v38, v37, v74
	v_mul_f32_e32 v36, v72, v36
	v_sub_f32_e32 v38, v73, v38
	v_add_f32_e32 v38, v38, v36
	v_add_f32_e32 v40, v37, v38
	v_mul_f32_e32 v41, v40, v40
	v_fmamk_f32 v36, v41, 0x3e9b6dac, v153
	v_fmaak_f32 v53, v41, v36, 0x3f2aaada
	v_cvt_f32_i32_e32 v36, v70
	v_sub_f32_e32 v37, v40, v37
	v_sub_f32_e32 v37, v38, v37
	v_ldexp_f32 v42, v37, 1
	v_mul_f32_e32 v37, v40, v41
	v_ldexp_f32 v39, v40, 1
	v_pk_mul_f32 v[40:41], v[36:37], v[52:53]
	s_nop 0
	v_fma_f32 v38, v36, s18, -v40
	v_fmac_f32_e32 v38, 0xb102e308, v36
	v_pk_add_f32 v[36:37], v[40:41], v[38:39]
	s_mov_b32 s18, 0x7f800000
	v_sub_f32_e32 v39, v37, v39
	v_sub_f32_e32 v39, v41, v39
	v_add_f32_e32 v43, v42, v39
	v_mov_b32_e32 v42, v40
	v_pk_add_f32 v[40:41], v[36:37], v[40:41] neg_lo:[0,1] neg_hi:[0,1]
	v_pk_add_f32 v[70:71], v[36:37], v[42:43]
	v_mov_b32_e32 v39, v36
	v_mov_b32_e32 v41, v71
	v_pk_add_f32 v[72:73], v[38:39], v[40:41] neg_lo:[0,1] neg_hi:[0,1]
	v_pk_add_f32 v[38:39], v[38:39], v[40:41]
	v_mov_b32_e32 v42, v43
	v_pk_add_f32 v[40:41], v[38:39], v[36:37] op_sel:[1,0] op_sel_hi:[0,1] neg_lo:[0,1] neg_hi:[0,1]
	v_pk_add_f32 v[74:75], v[70:71], v[40:41] op_sel_hi:[1,0] neg_lo:[0,1] neg_hi:[0,1]
	v_mov_b32_e32 v70, v71
	v_mov_b32_e32 v71, v39
	v_pk_mov_b32 v[40:41], v[36:37], v[40:41] op_sel:[1,0]
	v_mov_b32_e32 v43, v36
	v_pk_add_f32 v[40:41], v[70:71], v[40:41] neg_lo:[0,1] neg_hi:[0,1]
	v_mov_b32_e32 v74, v72
	v_pk_add_f32 v[36:37], v[42:43], v[40:41] neg_lo:[0,1] neg_hi:[0,1]
	v_mov_b32_e32 v73, v39
	v_pk_add_f32 v[40:41], v[74:75], v[36:37]
	v_cmp_neq_f32_e32 vcc, s18, v46
	v_pk_add_f32 v[42:43], v[40:41], v[40:41] op_sel:[0,1] op_sel_hi:[1,0]
	s_mov_b32 s18, 0x33800000
	v_pk_add_f32 v[38:39], v[38:39], v[42:43] op_sel:[1,0] op_sel_hi:[0,1]
	v_mov_b32_e32 v41, v38
	v_pk_add_f32 v[70:71], v[40:41], v[72:73] neg_lo:[0,1] neg_hi:[0,1]
	v_mov_b32_e32 v37, v42
	v_sub_f32_e32 v39, v40, v70
	v_pk_add_f32 v[36:37], v[36:37], v[70:71] neg_lo:[0,1] neg_hi:[0,1]
	v_sub_f32_e32 v39, v72, v39
	v_add_f32_e32 v36, v36, v39
	v_add_f32_e32 v36, v36, v37
	v_add_f32_e32 v36, v38, v36
	v_cndmask_b32_e32 v36, v161, v36, vcc
	v_cmp_ngt_f32_e32 vcc, -1.0, v46
	s_nop 1
	v_cndmask_b32_e32 v36, v162, v36, vcc
	v_cmp_neq_f32_e32 vcc, -1.0, v46
	s_nop 1
	v_cndmask_b32_e32 v36, v163, v36, vcc
	v_cmp_lt_f32_e64 vcc, |v46|, s18
	s_nop 1
	v_cndmask_b32_e32 v36, v36, v46, vcc

; __device__ __forceinline__ void ssd_phase(const Args& A, unsigned char* smem, const bool dry) {
;     ...
;                 if (bt + 1 < 64) { SSD_ISSUE(bt + 1); }
.LBB0_474:
	s_or_b64 exec, exec, s[74:75]
	s_cmpk_eq_i32 s23, 0xfc0
	s_cbranch_scc1 .LBB0_478
	s_waitcnt vmcnt(5)
	v_add_u32_e32 v0, s23, v149
	v_add_u32_e32 v1, s22, v150
	v_add_u32_e32 v2, s23, v147
	v_add_u32_e32 v3, s22, v148
	s_waitcnt vmcnt(3)
	v_add_u32_e32 v8, s23, v145
	v_add_u32_e32 v9, s22, v146
	v_add_u32_e32 v10, s23, v143
	v_add_u32_e32 v11, s22, v144
	s_waitcnt vmcnt(1)
	v_add_u32_e32 v16, s23, v141
	v_add_u32_e32 v17, s22, v142
	v_cndmask_b32_e64 v0, v1, v0, s[92:93]
	v_cndmask_b32_e64 v2, v3, v2, s[92:93]
	v_cndmask_b32_e64 v8, v9, v8, s[92:93]
	v_cndmask_b32_e64 v10, v11, v10, s[92:93]
	v_cndmask_b32_e64 v16, v17, v16, s[92:93]
	v_add_u32_e32 v0, s40, v0
	v_add_u32_e32 v2, s40, v2
	v_add_u32_e32 v8, s40, v8
	v_add_u32_e32 v10, s40, v10
	v_add_u32_e32 v16, s40, v16
	v_mad_i64_i32 v[0:1], s[14:15], v0, s33, v[58:59]
	v_mad_i64_i32 v[4:5], s[14:15], v2, s33, v[60:61]
	v_mad_i64_i32 v[8:9], s[14:15], v8, s33, v[62:63]
	v_mad_i64_i32 v[12:13], s[14:15], v10, s33, v[64:65]
	v_mad_i64_i32 v[16:17], s[14:15], v16, s33, v[66:67]
	global_load_dwordx4 v[0:3], v[0:1], off
	s_nop 0
	global_load_dwordx4 v[4:7], v[4:5], off
	s_nop 0
	global_load_dwordx4 v[8:11], v[8:9], off
	s_nop 0
	global_load_dwordx4 v[12:15], v[12:13], off
	s_nop 0
	global_load_dwordx4 v[16:19], v[16:17], off
	s_and_saveexec_b64 s[14:15], s[0:1]
	s_cbranch_execz .LBB0_477
	s_waitcnt lgkmcnt(0)
	v_add_u32_e32 v36, s22, v151
	v_add_u32_e32 v37, s23, v140
	v_cndmask_b32_e64 v36, v36, v37, s[92:93]
	v_add_u32_e32 v36, s40, v36
	v_ashrrev_i32_e32 v37, 31, v36
	v_lshlrev_b64 v[36:37], 7, v[36:37]
	v_lshl_add_u64 v[36:37], v[68:69], 0, v[36:37]
	global_load_dword v167, v[36:37], off

; #define LRU_ISSUE(BT) do { _Pragma("unroll") for (int k = 0; k < 2; ++k) { const int i_ = si + 64 * k; const int t_ = dir ? (SEQ - 1 - ((BT) * 128 + i_)) : ((BT) * 128 + i_); \
;         lpre[k] = *(const u32x4*)(proj + (size_t)(b * SEQ + t_) * PLD + 2048 + 64 * nb + c8); } } while (0)
; __device__ __forceinline__ void lru_phase(const Args& A, unsigned char* smem, const bool dry) {
;     ...
;             u32x4 lpre[2];
;     ...
;             LRU_ISSUE(0);
;             for (int bt = 0; bt < 32; ++bt) {
.LBB0_503:
	s_or_b64 exec, exec, s[8:9]
	v_cndmask_b32_e64 v0, v71, v82, s[16:17]
	v_or_b32_e32 v2, s47, v0
	v_mov_b64_e32 v[0:1], s[96:97]
	v_mad_i64_i32 v[2:3], s[8:9], v2, s39, v[0:1]
	s_lshl_b32 s12, s46, 1
	v_cndmask_b32_e64 v4, v73, v72, s[16:17]
	v_lshl_add_u64 v[2:3], v[2:3], 0, s[12:13]
	v_mov_b32_e32 v47, v43
	v_or_b32_e32 v4, s47, v4
	v_lshl_add_u64 v[2:3], v[2:3], 0, v[46:47]
	v_mad_i64_i32 v[0:1], s[8:9], v4, s39, v[0:1]
	v_add_co_u32_e32 v2, vcc, 0x1000, v2
	v_lshl_add_u64 v[0:1], v[0:1], 0, s[12:13]
	s_nop 0
	v_addc_co_u32_e32 v3, vcc, 0, v3, vcc
	v_lshl_add_u64 v[0:1], v[0:1], 0, v[46:47]
	v_add_co_u32_e32 v4, vcc, 0x1000, v0
	s_mov_b32 s49, 0
	s_nop 0
	v_addc_co_u32_e32 v5, vcc, 0, v1, vcc
	global_load_dwordx4 v[0:3], v[2:3], off
	s_nop 0
	global_load_dwordx4 v[4:7], v[4:5], off
	v_mov_b32_e32 v59, v58
	v_mov_b32_e32 v57, v56
	v_mov_b32_e32 v55, v54
	v_mov_b32_e32 v53, v52
	s_waitcnt vmcnt(0)
	s_branch .LBB0_505

; #define LRU_ISSUE(BT) do { _Pragma("unroll") for (int k = 0; k < 2; ++k) { const int i_ = si + 64 * k; const int t_ = dir ? (SEQ - 1 - ((BT) * 128 + i_)) : ((BT) * 128 + i_); \
;         lpre[k] = *(const u32x4*)(proj + (size_t)(b * SEQ + t_) * PLD + 2048 + 64 * nb + c8); } } while (0)
; __device__ __forceinline__ void lru_phase(const Args& A, unsigned char* smem, const bool dry) {
;     ...
;             LRU_ISSUE(0);
;             for (int bt = 0; bt < 32; ++bt) {
;                 *(u32x4*)(ub + si * 72 + c8) = lpre[0]; *(u32x4*)(ub + (si + 64) * 72 + c8) = lpre[1];
;                 if (bt + 1 < 32) { LRU_ISSUE(bt + 1); }
.LBB0_505:
	s_add_i32 s48, s49, 1
	s_cmp_eq_u32 s49, 31
	s_waitcnt vmcnt(3)
	ds_write_b128 v64, v[0:3] offset:18432
	s_waitcnt vmcnt(2)
	ds_write_b128 v64, v[4:7] offset:27648
	s_cbranch_scc1 .LBB0_507
	s_lshl_b32 s10, s48, 7
	v_or_b32_e32 v0, s10, v82
	v_sub_u32_e32 v1, 0xfff, v0
	v_cndmask_b32_e64 v0, v1, v0, s[16:17]
	v_add_u32_e32 v4, s10, v72
	v_add_u32_e32 v2, s47, v0
	v_mov_b64_e32 v[0:1], s[96:97]
	v_sub_u32_e32 v5, 0xfff, v4
	v_mad_i64_i32 v[2:3], s[8:9], v2, s39, v[0:1]
	v_cndmask_b32_e64 v4, v5, v4, s[16:17]
	v_lshl_add_u64 v[2:3], v[2:3], 0, s[12:13]
	v_mov_b32_e32 v47, v43
	v_add_u32_e32 v4, s47, v4
	v_lshl_add_u64 v[2:3], v[2:3], 0, v[46:47]
	v_mad_i64_i32 v[0:1], s[8:9], v4, s39, v[0:1]
	v_add_co_u32_e32 v2, vcc, 0x1000, v2
	v_lshl_add_u64 v[0:1], v[0:1], 0, s[12:13]
	s_nop 0
	v_addc_co_u32_e32 v3, vcc, 0, v3, vcc
	v_lshl_add_u64 v[0:1], v[0:1], 0, v[46:47]
	v_add_co_u32_e32 v4, vcc, 0x1000, v0
	s_nop 1
	v_addc_co_u32_e32 v5, vcc, 0, v1, vcc
	global_load_dwordx4 v[0:3], v[2:3], off
	s_nop 0
	global_load_dwordx4 v[4:7], v[4:5], off
